# v13 + in-proj gelu epilogue: the two consecutive constant multiplies before exp folded into one (192 instructions removed)
# baseline (speedup 1.0000x reference)
; __device__ __forceinline__ float gelu_f(float v) { const float u = 1.5957691216057308f * (v + 0.044715f * v * v * v); return v * fast_sigmoid(u); }
; __device__ __forceinline__ u32x4 pack8(const f32x4 a, const f32x4 b) { u32x4 w; w.x = cvt_pk_bf16(a[0], a[1]); w.y = cvt_pk_bf16(a[2], a[3]); w.z = cvt_pk_bf16(b[0], b[1]); w.w = cvt_pk_bf16(b[2], b[3]); return w; }
;     __device__ __forceinline__ void operator()(const Acc& acc, const Unit& u, int wr, int wc, int fr, int fq) const {
;     ...
;                 for (int m = 0; m < 4; ++m) {
;                     const int row = u.pm * 256 + ai * 128 + wr * 64 + m * 16 + fr;
;                     float s = 0.f, ss = 0.f;
; #pragma unroll
;                     for (int bj = 0; bj < 2; ++bj) {
;                         f32x4 v0 = acc[ai][bj][m][0], v1 = acc[ai][bj][m][1];
; #pragma unroll
;                         for (int j = 0; j < 4; ++j) { v0[j] = gelu_f(v0[j]); v1[j] = gelu_f(v1[j]); }
; #pragma unroll
;                         for (int j = 0; j < 4; ++j) { s += v0[j] + v1[j]; ss += v0[j] * v0[j] + v1[j] * v1[j]; }
;                         *(u32x4*)(GV + (size_t)row * DM + cb + bj * 128) = pack8(v0, v1);
;                     }
;                     s += __shfl_xor(s, 16); s += __shfl_xor(s, 32); ss += __shfl_xor(ss, 16); ss += __shfl_xor(ss, 32);
;                     if (fq == 0) *(f32x2*)(stats + ((size_t)row * 32 + pnv * 4 + wc) * 2) = (f32x2){s, ss};
.LBB0_161:
	v_fma_f32 v148, v124, v169, v124
	v_mul_f32_e32 v148, 0xc0135761, v148
	v_exp_f32_e32 v150, v148
	v_fma_f32 v148, v120, v168, v120
	v_mul_f32_e32 v148, 0xc0135761, v148
	v_fma_f32 v170, v125, v167, v125
	v_exp_f32_e32 v151, v148
	v_mul_f32_e32 v170, 0xc0135761, v170
	v_fma_f32 v174, v126, v165, v126
	v_mul_f32_e32 v174, 0xc0135761, v174
	v_exp_f32_e32 v172, v170
	v_fma_f32 v170, v121, v166, v121
	v_mul_f32_e32 v170, 0xc0135761, v170
	v_exp_f32_e32 v175, v174
	v_fma_f32 v174, v122, v163, v122
	v_add_f32_e32 v150, 1.0, v150
	v_add_f32_e32 v151, 1.0, v151
	v_mul_f32_e32 v174, 0xc0135761, v174
	v_rcp_f32_e32 v150, v150
	v_rcp_f32_e32 v151, v151
	v_exp_f32_e32 v173, v170
	v_exp_f32_e32 v176, v174
	v_mov_b32_e32 v152, v124
	v_mov_b32_e32 v153, v120
	v_pk_mul_f32 v[170:171], v[152:153], v[150:151]
	v_add_f32_e32 v173, 1.0, v173
	v_rcp_f32_e32 v174, v173
	v_add_f32_e32 v173, 1.0, v175
	v_add_f32_e32 v175, 1.0, v176
	v_fma_f32 v176, v127, v162, v127
	v_pk_fma_f32 v[150:151], v[152:153], v[150:151], v[170:171] op_sel:[0,0,1] op_sel_hi:[1,1,0]
	v_mul_f32_e32 v176, 0xc0135761, v176
	v_fma_f32 v177, v123, v161, v123
	v_mul_f32_e32 v151, 0x3d372713, v116
	v_mul_f32_e32 v177, 0xc0135761, v177
	v_mul_f32_e32 v151, v116, v151
	v_exp_f32_e32 v176, v176
	v_fma_f32 v151, v116, v151, v116
	v_exp_f32_e32 v177, v177
	v_mul_f32_e32 v151, 0xc0135761, v151
	v_mul_f32_e32 v152, 0x3d372713, v112
	v_mul_f32_e32 v152, v112, v152
	s_add_i32 s18, s70, -16
	v_ashrrev_i32_e32 v147, 31, v146
	v_exp_f32_e32 v151, v151
	v_fma_f32 v152, v112, v152, v112
	v_lshl_or_b32 v136, s18, 8, v156
	v_lshlrev_b64 v[148:149], 12, v[146:147]
	v_add_f32_e32 v176, 1.0, v176
	v_mul_f32_e32 v152, 0xc0135761, v152
	v_rcp_f32_e32 v179, v176
	v_add_f32_e32 v176, 1.0, v177
	v_lshl_add_u64 v[148:149], s[10:11], 0, v[148:149]
	v_lshlrev_b32_e32 v136, 1, v136
	v_rcp_f32_e32 v177, v176
	v_exp_f32_e32 v176, v152
	v_lshl_add_u64 v[152:153], v[148:149], 0, v[136:137]
	v_mul_f32_e32 v149, 0x3d372713, v117
	v_add_f32_e32 v148, 1.0, v151
	v_mul_f32_e32 v149, v117, v149
	v_mul_f32_e32 v151, 0x3d372713, v113
	v_fma_f32 v149, v117, v149, v117
	v_mul_f32_e32 v151, v113, v151
	v_mul_f32_e32 v149, 0xc0135761, v149
	v_fma_f32 v151, v113, v151, v113
	v_mul_f32_e32 v151, 0xc0135761, v151
	v_exp_f32_e32 v149, v149
	v_exp_f32_e32 v151, v151
	v_rcp_f32_e32 v188, v148
	v_add_f32_e32 v148, 1.0, v176
	v_rcp_f32_e32 v189, v148
	v_add_f32_e32 v148, 1.0, v149
	v_mul_f32_e32 v149, 0x3d372713, v118
	v_rcp_f32_e32 v190, v148
	v_add_f32_e32 v148, 1.0, v151
	v_mul_f32_e32 v149, v118, v149
	v_mul_f32_e32 v151, 0x3d372713, v114
	v_fma_f32 v149, v118, v149, v118
	v_mul_f32_e32 v151, v114, v151
	v_mul_f32_e32 v149, 0xc0135761, v149
	v_fma_f32 v151, v114, v151, v114
	v_mul_f32_e32 v151, 0xc0135761, v151
	v_exp_f32_e32 v149, v149
	v_exp_f32_e32 v151, v151
	v_rcp_f32_e32 v191, v148
	v_add_f32_e32 v148, 1.0, v149
	v_mul_f32_e32 v149, 0x3d372713, v119
	v_rcp_f32_e32 v192, v148
	v_add_f32_e32 v148, 1.0, v151
	v_mul_f32_e32 v149, v119, v149
	v_mul_f32_e32 v151, 0x3d372713, v115
	v_fma_f32 v149, v119, v149, v119
	v_mul_f32_e32 v151, v115, v151
	v_mul_f32_e32 v149, 0xc0135761, v149
	v_fma_f32 v151, v115, v151, v115
	v_mul_f32_e32 v151, 0xc0135761, v151
	v_exp_f32_e32 v149, v149
	v_exp_f32_e32 v151, v151
	v_add_f32_e32 v172, 1.0, v172
	v_rcp_f32_e32 v173, v173
	v_rcp_f32_e32 v175, v175
	v_rcp_f32_e32 v172, v172
	v_rcp_f32_e32 v193, v148
	v_add_f32_e32 v148, 1.0, v149
	v_rcp_f32_e32 v194, v148
	v_add_f32_e32 v148, 1.0, v151
	v_rcp_f32_e32 v195, v148
	v_mul_f32_e32 v176, v126, v173
	v_mul_f32_e32 v178, v122, v175
	v_mov_b32_e32 v148, v125
	v_mov_b32_e32 v149, v170
	v_mov_b32_e32 v173, v170
	v_mov_b32_e32 v186, v121
	v_mov_b32_e32 v187, v171
	v_mov_b32_e32 v175, v171
	v_pk_mul_f32 v[184:185], v[148:149], v[172:173]
	v_pk_mul_f32 v[174:175], v[186:187], v[174:175]
	v_mul_f32_e32 v180, v127, v179
	v_pk_fma_f32 v[148:149], v[148:149], v[172:173], v[174:175]
	v_pk_mul_f32 v[172:173], v[184:185], v[184:185]
	v_pk_mul_f32 v[186:187], v[174:175], v[174:175]
	v_mov_b32_e32 v151, v172
	v_mov_b32_e32 v172, v137
	v_mov_b32_e32 v173, v186
	v_mul_f32_e32 v182, v123, v177
	v_pk_add_f32 v[150:151], v[150:151], v[172:173]
	v_mul_f32_e32 v177, v176, v176
	v_mul_f32_e32 v179, v178, v178
	v_pk_add_f32 v[148:149], v[148:149], v[150:151]
	v_pk_add_f32 v[150:151], v[176:177], v[178:179]
	v_mul_f32_e32 v181, v180, v180
	v_mul_f32_e32 v183, v182, v182
	v_pk_add_f32 v[148:149], v[150:151], v[148:149]
	v_pk_add_f32 v[150:151], v[180:181], v[182:183]
	v_mul_f32_e32 v172, v116, v188
	v_pk_add_f32 v[150:151], v[150:151], v[148:149]
	v_cvt_pk_bf16_f32 v148, v170, v184
	v_cvt_pk_bf16_f32 v149, v176, v180
	v_mul_f32_e32 v176, v112, v189
	v_mul_f32_e32 v180, v117, v190
	v_mul_f32_e32 v184, v113, v191
	v_mul_f32_e32 v173, v172, v172
	v_mul_f32_e32 v177, v176, v176
	v_mul_f32_e32 v186, v118, v192
	v_mul_f32_e32 v188, v114, v193
	v_mul_f32_e32 v190, v119, v194
	v_mul_f32_e32 v192, v115, v195
	v_pk_add_f32 v[194:195], v[172:173], v[176:177]
	v_mul_f32_e32 v181, v180, v180
	v_mul_f32_e32 v185, v184, v184
	v_pk_add_f32 v[150:151], v[150:151], v[194:195]
	v_pk_add_f32 v[194:195], v[180:181], v[184:185]
	v_mul_f32_e32 v187, v186, v186
	v_mul_f32_e32 v189, v188, v188
	v_pk_add_f32 v[150:151], v[194:195], v[150:151]
	v_pk_add_f32 v[194:195], v[186:187], v[188:189]
	v_mul_f32_e32 v191, v190, v190
	v_mul_f32_e32 v193, v192, v192
	v_pk_add_f32 v[150:151], v[194:195], v[150:151]
	v_pk_add_f32 v[194:195], v[190:191], v[192:193]
	s_lshl_b32 s18, s18, 2
	v_pk_add_f32 v[194:195], v[194:195], v[150:151]
	v_and_b32_e32 v151, 64, v160
	v_xor_b32_e32 v150, 16, v160
	v_add_u32_e32 v173, 64, v151
	v_cmp_lt_i32_e32 vcc, v150, v173
	s_or_b32 s18, s18, s81
	s_nop 0
	v_cndmask_b32_e32 v150, v160, v150, vcc
	v_lshlrev_b32_e32 v170, 2, v150
	ds_bpermute_b32 v196, v170, v194
	ds_bpermute_b32 v197, v170, v195
	v_cvt_pk_bf16_f32 v150, v171, v174
	v_cvt_pk_bf16_f32 v151, v178, v182
	global_store_dwordx4 v[152:153], v[148:151], off
	v_cvt_pk_bf16_f32 v172, v172, v180
	s_nop 1
	v_xor_b32_e32 v150, 32, v160
	v_cmp_lt_i32_e32 vcc, v150, v173
	s_waitcnt lgkmcnt(0)
	v_pk_add_f32 v[148:149], v[194:195], v[196:197]
	v_cvt_pk_bf16_f32 v173, v186, v190
	v_cvt_pk_bf16_f32 v174, v176, v184
	v_cvt_pk_bf16_f32 v175, v188, v192
	global_store_dwordx4 v[152:153], v[172:175], off offset:256
	v_cndmask_b32_e32 v150, v160, v150, vcc
	v_lshlrev_b32_e32 v171, 2, v150
	ds_bpermute_b32 v150, v171, v148
	ds_bpermute_b32 v151, v171, v149
	s_and_saveexec_b64 s[72:73], s[4:5]
	s_cbranch_execz .LBB0_163
	v_lshlrev_b64 v[152:153], 8, v[146:147]
	s_waitcnt lgkmcnt(0)
	v_pk_add_f32 v[148:149], v[148:149], v[150:151]
	v_lshl_add_u64 v[150:151], s[16:17], 0, v[152:153]
	v_lshl_add_u64 v[150:151], s[18:19], 3, v[150:151]
	global_store_dwordx2 v[150:151], v[148:149], off
; __device__ __forceinline__ float gelu_f(float v) { const float u = 1.5957691216057308f * (v + 0.044715f * v * v * v); return v * fast_sigmoid(u); }
; __device__ __forceinline__ u32x4 pack8(const f32x4 a, const f32x4 b) { u32x4 w; w.x = cvt_pk_bf16(a[0], a[1]); w.y = cvt_pk_bf16(a[2], a[3]); w.z = cvt_pk_bf16(b[0], b[1]); w.w = cvt_pk_bf16(b[2], b[3]); return w; }
;     __device__ __forceinline__ void operator()(const Acc& acc, const Unit& u, int wr, int wc, int fr, int fq) const {
;     ...
;                 for (int m = 0; m < 4; ++m) {
;                     const int row = u.pm * 256 + ai * 128 + wr * 64 + m * 16 + fr;
;                     float s = 0.f, ss = 0.f;
; #pragma unroll
;                     for (int bj = 0; bj < 2; ++bj) {
;                         f32x4 v0 = acc[ai][bj][m][0], v1 = acc[ai][bj][m][1];
; #pragma unroll
;                         for (int j = 0; j < 4; ++j) { v0[j] = gelu_f(v0[j]); v1[j] = gelu_f(v1[j]); }
; #pragma unroll
;                         for (int j = 0; j < 4; ++j) { s += v0[j] + v1[j]; ss += v0[j] * v0[j] + v1[j] * v1[j]; }
;                         *(u32x4*)(GV + (size_t)row * DM + cb + bj * 128) = pack8(v0, v1);
;                     }
;                     s += __shfl_xor(s, 16); s += __shfl_xor(s, 32); ss += __shfl_xor(ss, 16); ss += __shfl_xor(ss, 32);
;                     if (fq == 0) *(f32x2*)(stats + ((size_t)row * 32 + pnv * 4 + wc) * 2) = (f32x2){s, ss};
.LBB0_163:
	s_or_b64 exec, exec, s[72:73]
	v_mul_f32_e32 v147, 0x3d372713, v108
	v_mul_f32_e32 v147, v108, v147
	s_waitcnt lgkmcnt(0)
	v_mul_f32_e32 v150, 0x3d372713, v104
	v_fma_f32 v147, v108, v147, v108
	v_mul_f32_e32 v150, v104, v150
	v_mul_f32_e32 v147, 0xc0135761, v147
	v_fma_f32 v150, v104, v150, v104
	v_mul_f32_e32 v150, 0xc0135761, v150
	v_exp_f32_e32 v147, v147
	v_exp_f32_e32 v153, v150
	v_mul_f32_e32 v174, 0x3d372713, v105
	v_add_f32_e32 v147, 1.0, v147
	v_rcp_f32_e32 v152, v147
	v_add_f32_e32 v147, 1.0, v153
	v_rcp_f32_e32 v153, v147
	v_mul_f32_e32 v174, v105, v174
	v_fma_f32 v174, v105, v174, v105
	v_mul_f32_e32 v174, 0xc0135761, v174
	v_mov_b32_e32 v172, v108
	v_mov_b32_e32 v173, v104
	v_exp_f32_e32 v177, v174
	v_pk_mul_f32 v[174:175], v[172:173], v[152:153]
	v_mul_f32_e32 v180, 0x3d372713, v107
	v_mul_f32_e32 v180, v107, v180
	v_pk_fma_f32 v[152:153], v[172:173], v[152:153], v[174:175] op_sel:[0,0,1] op_sel_hi:[1,1,0]
	v_fma_f32 v180, v107, v180, v107
	v_mul_f32_e32 v153, 0x3d372713, v100
	v_mul_f32_e32 v180, 0xc0135761, v180
	v_mul_f32_e32 v153, v100, v153
	v_fma_f32 v153, v100, v153, v100
	v_exp_f32_e32 v180, v180
	v_mul_f32_e32 v153, 0xc0135761, v153
	v_or_b32_e32 v148, 16, v146
	v_mul_f32_e32 v147, 0x3d372713, v109
	v_ashrrev_i32_e32 v149, 31, v148
	v_mul_f32_e32 v147, v109, v147
	v_exp_f32_e32 v153, v153
	v_lshlrev_b64 v[150:151], 12, v[148:149]
	v_fma_f32 v147, v109, v147, v109
	v_mul_f32_e32 v147, 0xc0135761, v147
	v_add_f32_e32 v180, 1.0, v180
	v_lshl_add_u64 v[150:151], s[10:11], 0, v[150:151]
	v_mul_f32_e32 v172, 0x3d372713, v96
	v_rcp_f32_e32 v183, v180
	v_mul_f32_e32 v172, v96, v172
	v_lshl_add_u64 v[180:181], v[150:151], 0, v[136:137]
	v_mul_f32_e32 v151, 0x3d372713, v101
	v_exp_f32_e32 v147, v147
	v_fma_f32 v172, v96, v172, v96
	v_add_f32_e32 v150, 1.0, v153
	v_mul_f32_e32 v151, v101, v151
	v_mul_f32_e32 v153, 0x3d372713, v97
	v_mul_f32_e32 v172, 0xc0135761, v172
	v_fma_f32 v151, v101, v151, v101
	v_mul_f32_e32 v153, v97, v153
	v_mul_f32_e32 v151, 0xc0135761, v151
	v_fma_f32 v153, v97, v153, v97
	v_exp_f32_e32 v172, v172
	v_mul_f32_e32 v153, 0xc0135761, v153
	v_add_f32_e32 v147, 1.0, v147
	v_exp_f32_e32 v151, v151
	v_rcp_f32_e32 v176, v147
	v_add_f32_e32 v147, 1.0, v177
	v_mul_f32_e32 v177, 0x3d372713, v110
	v_mul_f32_e32 v178, 0x3d372713, v106
	v_exp_f32_e32 v153, v153
	v_mul_f32_e32 v177, v110, v177
	v_mul_f32_e32 v178, v106, v178
	v_fma_f32 v177, v110, v177, v110
	v_fma_f32 v178, v106, v178, v106
	v_rcp_f32_e32 v192, v150
	v_add_f32_e32 v150, 1.0, v172
	v_mul_f32_e32 v177, 0xc0135761, v177
	v_mul_f32_e32 v178, 0xc0135761, v178
	v_rcp_f32_e32 v193, v150
	v_add_f32_e32 v150, 1.0, v151
	v_mul_f32_e32 v151, 0x3d372713, v102
	v_rcp_f32_e32 v194, v150
	v_add_f32_e32 v150, 1.0, v153
	v_mul_f32_e32 v151, v102, v151
	v_mul_f32_e32 v153, 0x3d372713, v98
	v_exp_f32_e32 v177, v177
	v_exp_f32_e32 v179, v178
	v_fma_f32 v151, v102, v151, v102
	v_mul_f32_e32 v153, v98, v153
	v_mul_f32_e32 v151, 0xc0135761, v151
	v_fma_f32 v153, v98, v153, v98
	v_mul_f32_e32 v153, 0xc0135761, v153
	v_exp_f32_e32 v151, v151
	v_rcp_f32_e32 v178, v147
	v_add_f32_e32 v147, 1.0, v177
	v_add_f32_e32 v177, 1.0, v179
	v_mul_f32_e32 v179, 0x3d372713, v111
	v_exp_f32_e32 v153, v153
	v_mul_f32_e32 v179, v111, v179
	v_fma_f32 v179, v111, v179, v111
	v_mul_f32_e32 v179, 0xc0135761, v179
	v_rcp_f32_e32 v195, v150
	v_add_f32_e32 v150, 1.0, v151
	v_mul_f32_e32 v151, 0x3d372713, v103
	v_rcp_f32_e32 v196, v150
	v_add_f32_e32 v150, 1.0, v153
	v_mul_f32_e32 v151, v103, v151
	v_mul_f32_e32 v153, 0x3d372713, v99
	v_exp_f32_e32 v179, v179
	v_fma_f32 v151, v103, v151, v103
	v_mul_f32_e32 v153, v99, v153
	v_mul_f32_e32 v151, 0xc0135761, v151
	v_fma_f32 v153, v99, v153, v99
	v_mul_f32_e32 v153, 0xc0135761, v153
	v_exp_f32_e32 v151, v151
	v_add_f32_e32 v179, 1.0, v179
	v_exp_f32_e32 v153, v153
	v_rcp_f32_e32 v177, v177
	v_rcp_f32_e32 v179, v179
	v_rcp_f32_e32 v197, v150
	v_add_f32_e32 v150, 1.0, v151
	v_rcp_f32_e32 v147, v147
	v_rcp_f32_e32 v198, v150
	v_add_f32_e32 v150, 1.0, v153
	v_rcp_f32_e32 v199, v150
	v_mul_f32_e32 v182, v106, v177
	v_mul_f32_e32 v184, v111, v179
	v_mov_b32_e32 v150, v109
	v_mov_b32_e32 v151, v174
	v_mov_b32_e32 v177, v174
	v_mov_b32_e32 v190, v105
	v_mov_b32_e32 v191, v175
	v_mov_b32_e32 v179, v175
	v_pk_mul_f32 v[188:189], v[150:151], v[176:177]
	v_pk_mul_f32 v[178:179], v[190:191], v[178:179]
	v_mul_f32_e32 v172, v110, v147
	v_pk_fma_f32 v[150:151], v[150:151], v[176:177], v[178:179]
	v_pk_mul_f32 v[176:177], v[188:189], v[188:189]
	v_pk_mul_f32 v[190:191], v[178:179], v[178:179]
	v_mov_b32_e32 v153, v176
	v_mov_b32_e32 v176, v137
	v_mov_b32_e32 v177, v190
	v_mul_f32_e32 v186, v107, v183
	v_pk_add_f32 v[152:153], v[152:153], v[176:177]
	v_mul_f32_e32 v173, v172, v172
	v_mul_f32_e32 v183, v182, v182
	v_pk_add_f32 v[150:151], v[150:151], v[152:153]
	v_pk_add_f32 v[152:153], v[172:173], v[182:183]
	v_mul_f32_e32 v185, v184, v184
	v_mul_f32_e32 v187, v186, v186
	v_pk_add_f32 v[150:151], v[152:153], v[150:151]
	v_pk_add_f32 v[152:153], v[184:185], v[186:187]
	v_mul_f32_e32 v176, v96, v193
	v_pk_add_f32 v[152:153], v[152:153], v[150:151]
	v_cvt_pk_bf16_f32 v150, v174, v188
	v_cvt_pk_bf16_f32 v151, v172, v184
	v_mul_f32_e32 v172, v100, v192
	v_mul_f32_e32 v184, v101, v194
	v_mul_f32_e32 v188, v97, v195
	v_mul_f32_e32 v173, v172, v172
	v_mul_f32_e32 v177, v176, v176
	v_mul_f32_e32 v190, v102, v196
	v_mul_f32_e32 v192, v98, v197
	v_mul_f32_e32 v194, v103, v198
	v_mul_f32_e32 v196, v99, v199
	v_pk_add_f32 v[198:199], v[172:173], v[176:177]
	v_mul_f32_e32 v185, v184, v184
	v_mul_f32_e32 v189, v188, v188
	v_pk_add_f32 v[152:153], v[152:153], v[198:199]
	v_pk_add_f32 v[198:199], v[184:185], v[188:189]
	v_mul_f32_e32 v191, v190, v190
	v_mul_f32_e32 v193, v192, v192
	v_pk_add_f32 v[152:153], v[198:199], v[152:153]
	v_pk_add_f32 v[198:199], v[190:191], v[192:193]
	v_mul_f32_e32 v195, v194, v194
	v_mul_f32_e32 v197, v196, v196
	v_pk_add_f32 v[152:153], v[198:199], v[152:153]
	v_pk_add_f32 v[198:199], v[194:195], v[196:197]
	s_nop 0
	v_pk_add_f32 v[198:199], v[198:199], v[152:153]
	ds_bpermute_b32 v200, v170, v198
	ds_bpermute_b32 v201, v170, v199
	v_cvt_pk_bf16_f32 v152, v175, v178
	v_cvt_pk_bf16_f32 v153, v182, v186
	global_store_dwordx4 v[180:181], v[150:153], off
	v_cvt_pk_bf16_f32 v172, v172, v184
	v_cvt_pk_bf16_f32 v173, v190, v194
	v_cvt_pk_bf16_f32 v174, v176, v188
	v_cvt_pk_bf16_f32 v175, v192, v196
	global_store_dwordx4 v[180:181], v[172:175], off offset:256
	s_waitcnt lgkmcnt(0)
	v_pk_add_f32 v[150:151], v[198:199], v[200:201]
	ds_bpermute_b32 v152, v171, v150
	ds_bpermute_b32 v153, v171, v151
	s_and_saveexec_b64 s[72:73], s[4:5]
	s_cbranch_execz .LBB0_165
	v_lshlrev_b64 v[148:149], 8, v[148:149]
	v_lshl_add_u64 v[148:149], s[16:17], 0, v[148:149]
	s_waitcnt lgkmcnt(0)
	v_pk_add_f32 v[150:151], v[150:151], v[152:153]
	v_lshl_add_u64 v[148:149], s[18:19], 3, v[148:149]
	global_store_dwordx2 v[148:149], v[150:151], off
; __device__ __forceinline__ float gelu_f(float v) { const float u = 1.5957691216057308f * (v + 0.044715f * v * v * v); return v * fast_sigmoid(u); }
; __device__ __forceinline__ u32x4 pack8(const f32x4 a, const f32x4 b) { u32x4 w; w.x = cvt_pk_bf16(a[0], a[1]); w.y = cvt_pk_bf16(a[2], a[3]); w.z = cvt_pk_bf16(b[0], b[1]); w.w = cvt_pk_bf16(b[2], b[3]); return w; }
;     __device__ __forceinline__ void operator()(const Acc& acc, const Unit& u, int wr, int wc, int fr, int fq) const {
;     ...
;                 for (int m = 0; m < 4; ++m) {
;                     const int row = u.pm * 256 + ai * 128 + wr * 64 + m * 16 + fr;
;                     float s = 0.f, ss = 0.f;
; #pragma unroll
;                     for (int bj = 0; bj < 2; ++bj) {
;                         f32x4 v0 = acc[ai][bj][m][0], v1 = acc[ai][bj][m][1];
; #pragma unroll
;                         for (int j = 0; j < 4; ++j) { v0[j] = gelu_f(v0[j]); v1[j] = gelu_f(v1[j]); }
; #pragma unroll
;                         for (int j = 0; j < 4; ++j) { s += v0[j] + v1[j]; ss += v0[j] * v0[j] + v1[j] * v1[j]; }
;                         *(u32x4*)(GV + (size_t)row * DM + cb + bj * 128) = pack8(v0, v1);
;                     }
;                     s += __shfl_xor(s, 16); s += __shfl_xor(s, 32); ss += __shfl_xor(ss, 16); ss += __shfl_xor(ss, 32);
;                     if (fq == 0) *(f32x2*)(stats + ((size_t)row * 32 + pnv * 4 + wc) * 2) = (f32x2){s, ss};
.LBB0_165:
	s_or_b64 exec, exec, s[72:73]
	v_mul_f32_e32 v147, 0x3d372713, v92
	v_mul_f32_e32 v147, v92, v147
	v_mul_f32_e32 v150, 0x3d372713, v88
	v_fma_f32 v147, v92, v147, v92
	v_mul_f32_e32 v150, v88, v150
	v_mul_f32_e32 v147, 0xc0135761, v147
	v_fma_f32 v150, v88, v150, v88
	v_mul_f32_e32 v150, 0xc0135761, v150
	v_exp_f32_e32 v147, v147
	s_waitcnt lgkmcnt(0)
	v_exp_f32_e32 v153, v150
	v_mul_f32_e32 v174, 0x3d372713, v89
	v_add_f32_e32 v147, 1.0, v147
	v_rcp_f32_e32 v152, v147
	v_add_f32_e32 v147, 1.0, v153
	v_rcp_f32_e32 v153, v147
	v_mul_f32_e32 v174, v89, v174
	v_fma_f32 v174, v89, v174, v89
	v_mul_f32_e32 v174, 0xc0135761, v174
	v_mov_b32_e32 v172, v92
	v_mov_b32_e32 v173, v88
	v_exp_f32_e32 v177, v174
	v_pk_mul_f32 v[174:175], v[172:173], v[152:153]
	v_mul_f32_e32 v180, 0x3d372713, v91
	v_mul_f32_e32 v180, v91, v180
	v_pk_fma_f32 v[152:153], v[172:173], v[152:153], v[174:175] op_sel:[0,0,1] op_sel_hi:[1,1,0]
	v_fma_f32 v180, v91, v180, v91
	v_mul_f32_e32 v153, 0x3d372713, v84
	v_mul_f32_e32 v180, 0xc0135761, v180
	v_mul_f32_e32 v153, v84, v153
	v_fma_f32 v153, v84, v153, v84
	v_exp_f32_e32 v180, v180
	v_mul_f32_e32 v153, 0xc0135761, v153
	v_or_b32_e32 v148, 32, v146
	v_mul_f32_e32 v147, 0x3d372713, v93
	v_ashrrev_i32_e32 v149, 31, v148
	v_mul_f32_e32 v147, v93, v147
	v_exp_f32_e32 v153, v153
	v_lshlrev_b64 v[150:151], 12, v[148:149]
	v_fma_f32 v147, v93, v147, v93
	v_mul_f32_e32 v147, 0xc0135761, v147
	v_add_f32_e32 v180, 1.0, v180
	v_lshl_add_u64 v[150:151], s[10:11], 0, v[150:151]
	v_mul_f32_e32 v172, 0x3d372713, v80
	v_rcp_f32_e32 v183, v180
	v_mul_f32_e32 v172, v80, v172
	v_lshl_add_u64 v[180:181], v[150:151], 0, v[136:137]
	v_mul_f32_e32 v151, 0x3d372713, v85
	v_exp_f32_e32 v147, v147
	v_fma_f32 v172, v80, v172, v80
	v_add_f32_e32 v150, 1.0, v153
	v_mul_f32_e32 v151, v85, v151
	v_mul_f32_e32 v153, 0x3d372713, v81
	v_mul_f32_e32 v172, 0xc0135761, v172
	v_fma_f32 v151, v85, v151, v85
	v_mul_f32_e32 v153, v81, v153
	v_mul_f32_e32 v151, 0xc0135761, v151
	v_fma_f32 v153, v81, v153, v81
	v_exp_f32_e32 v172, v172
	v_mul_f32_e32 v153, 0xc0135761, v153
	v_add_f32_e32 v147, 1.0, v147
	v_exp_f32_e32 v151, v151
	v_rcp_f32_e32 v176, v147
	v_add_f32_e32 v147, 1.0, v177
	v_mul_f32_e32 v177, 0x3d372713, v94
	v_mul_f32_e32 v178, 0x3d372713, v90
	v_exp_f32_e32 v153, v153
	v_mul_f32_e32 v177, v94, v177
	v_mul_f32_e32 v178, v90, v178
	v_fma_f32 v177, v94, v177, v94
	v_fma_f32 v178, v90, v178, v90
	v_rcp_f32_e32 v192, v150
	v_add_f32_e32 v150, 1.0, v172
	v_mul_f32_e32 v177, 0xc0135761, v177
	v_mul_f32_e32 v178, 0xc0135761, v178
	v_rcp_f32_e32 v193, v150
	v_add_f32_e32 v150, 1.0, v151
	v_mul_f32_e32 v151, 0x3d372713, v86
	v_rcp_f32_e32 v194, v150
	v_add_f32_e32 v150, 1.0, v153
	v_mul_f32_e32 v151, v86, v151
	v_mul_f32_e32 v153, 0x3d372713, v82
	v_exp_f32_e32 v177, v177
	v_exp_f32_e32 v179, v178
	v_fma_f32 v151, v86, v151, v86
	v_mul_f32_e32 v153, v82, v153
	v_mul_f32_e32 v151, 0xc0135761, v151
	v_fma_f32 v153, v82, v153, v82
	v_mul_f32_e32 v153, 0xc0135761, v153
	v_exp_f32_e32 v151, v151
	v_rcp_f32_e32 v178, v147
	v_add_f32_e32 v147, 1.0, v177
	v_add_f32_e32 v177, 1.0, v179
	v_mul_f32_e32 v179, 0x3d372713, v95
	v_exp_f32_e32 v153, v153
	v_mul_f32_e32 v179, v95, v179
	v_fma_f32 v179, v95, v179, v95
	v_mul_f32_e32 v179, 0xc0135761, v179
	v_rcp_f32_e32 v195, v150
	v_add_f32_e32 v150, 1.0, v151
	v_mul_f32_e32 v151, 0x3d372713, v87
	v_rcp_f32_e32 v196, v150
	v_add_f32_e32 v150, 1.0, v153
	v_mul_f32_e32 v151, v87, v151
	v_mul_f32_e32 v153, 0x3d372713, v83
	v_exp_f32_e32 v179, v179
	v_fma_f32 v151, v87, v151, v87
	v_mul_f32_e32 v153, v83, v153
	v_mul_f32_e32 v151, 0xc0135761, v151
	v_fma_f32 v153, v83, v153, v83
	v_mul_f32_e32 v153, 0xc0135761, v153
	v_exp_f32_e32 v151, v151
	v_add_f32_e32 v179, 1.0, v179
	v_exp_f32_e32 v153, v153
	v_rcp_f32_e32 v177, v177
	v_rcp_f32_e32 v179, v179
	v_rcp_f32_e32 v197, v150
	v_add_f32_e32 v150, 1.0, v151
	v_rcp_f32_e32 v147, v147
	v_rcp_f32_e32 v198, v150
	v_add_f32_e32 v150, 1.0, v153
	v_rcp_f32_e32 v199, v150
	v_mul_f32_e32 v182, v90, v177
	v_mul_f32_e32 v184, v95, v179
	v_mov_b32_e32 v150, v93
	v_mov_b32_e32 v151, v174
	v_mov_b32_e32 v177, v174
	v_mov_b32_e32 v190, v89
	v_mov_b32_e32 v191, v175
	v_mov_b32_e32 v179, v175
	v_pk_mul_f32 v[188:189], v[150:151], v[176:177]
	v_pk_mul_f32 v[178:179], v[190:191], v[178:179]
	v_mul_f32_e32 v172, v94, v147
	v_pk_fma_f32 v[150:151], v[150:151], v[176:177], v[178:179]
	v_pk_mul_f32 v[176:177], v[188:189], v[188:189]
	v_pk_mul_f32 v[190:191], v[178:179], v[178:179]
	v_mov_b32_e32 v153, v176
	v_mov_b32_e32 v176, v137
	v_mov_b32_e32 v177, v190
	v_mul_f32_e32 v186, v91, v183
	v_pk_add_f32 v[152:153], v[152:153], v[176:177]
	v_mul_f32_e32 v173, v172, v172
	v_mul_f32_e32 v183, v182, v182
	v_pk_add_f32 v[150:151], v[150:151], v[152:153]
	v_pk_add_f32 v[152:153], v[172:173], v[182:183]
	v_mul_f32_e32 v185, v184, v184
	v_mul_f32_e32 v187, v186, v186
	v_pk_add_f32 v[150:151], v[152:153], v[150:151]
	v_pk_add_f32 v[152:153], v[184:185], v[186:187]
	v_mul_f32_e32 v176, v80, v193
	v_pk_add_f32 v[152:153], v[152:153], v[150:151]
	v_cvt_pk_bf16_f32 v150, v174, v188
	v_cvt_pk_bf16_f32 v151, v172, v184
	v_mul_f32_e32 v172, v84, v192
	v_mul_f32_e32 v184, v85, v194
	v_mul_f32_e32 v188, v81, v195
	v_mul_f32_e32 v173, v172, v172
	v_mul_f32_e32 v177, v176, v176
	v_mul_f32_e32 v190, v86, v196
	v_mul_f32_e32 v192, v82, v197
	v_mul_f32_e32 v194, v87, v198
	v_mul_f32_e32 v196, v83, v199
	v_pk_add_f32 v[198:199], v[172:173], v[176:177]
	v_mul_f32_e32 v185, v184, v184
	v_mul_f32_e32 v189, v188, v188
	v_pk_add_f32 v[152:153], v[152:153], v[198:199]
	v_pk_add_f32 v[198:199], v[184:185], v[188:189]
	v_mul_f32_e32 v191, v190, v190
	v_mul_f32_e32 v193, v192, v192
	v_pk_add_f32 v[152:153], v[198:199], v[152:153]
	v_pk_add_f32 v[198:199], v[190:191], v[192:193]
	v_mul_f32_e32 v195, v194, v194
	v_mul_f32_e32 v197, v196, v196
	v_pk_add_f32 v[152:153], v[198:199], v[152:153]
	v_pk_add_f32 v[198:199], v[194:195], v[196:197]
	s_nop 0
	v_pk_add_f32 v[198:199], v[198:199], v[152:153]
	ds_bpermute_b32 v200, v170, v198
	ds_bpermute_b32 v201, v170, v199
	v_cvt_pk_bf16_f32 v152, v175, v178
	v_cvt_pk_bf16_f32 v153, v182, v186
	global_store_dwordx4 v[180:181], v[150:153], off
	v_cvt_pk_bf16_f32 v172, v172, v184
	v_cvt_pk_bf16_f32 v173, v190, v194
	v_cvt_pk_bf16_f32 v174, v176, v188
	v_cvt_pk_bf16_f32 v175, v192, v196
	global_store_dwordx4 v[180:181], v[172:175], off offset:256
	s_waitcnt lgkmcnt(0)
	v_pk_add_f32 v[150:151], v[198:199], v[200:201]
	ds_bpermute_b32 v152, v171, v150
	ds_bpermute_b32 v153, v171, v151
	s_and_saveexec_b64 s[72:73], s[4:5]
	s_cbranch_execz .LBB0_167
	v_lshlrev_b64 v[148:149], 8, v[148:149]
	v_lshl_add_u64 v[148:149], s[16:17], 0, v[148:149]
	s_waitcnt lgkmcnt(0)
	v_pk_add_f32 v[150:151], v[150:151], v[152:153]
	v_lshl_add_u64 v[148:149], s[18:19], 3, v[148:149]
	global_store_dwordx2 v[148:149], v[150:151], off
; __device__ __forceinline__ float gelu_f(float v) { const float u = 1.5957691216057308f * (v + 0.044715f * v * v * v); return v * fast_sigmoid(u); }
; __device__ __forceinline__ u32x4 pack8(const f32x4 a, const f32x4 b) { u32x4 w; w.x = cvt_pk_bf16(a[0], a[1]); w.y = cvt_pk_bf16(a[2], a[3]); w.z = cvt_pk_bf16(b[0], b[1]); w.w = cvt_pk_bf16(b[2], b[3]); return w; }
;     __device__ __forceinline__ void operator()(const Acc& acc, const Unit& u, int wr, int wc, int fr, int fq) const {
;     ...
;                 for (int m = 0; m < 4; ++m) {
;                     const int row = u.pm * 256 + ai * 128 + wr * 64 + m * 16 + fr;
;                     float s = 0.f, ss = 0.f;
; #pragma unroll
;                     for (int bj = 0; bj < 2; ++bj) {
;                         f32x4 v0 = acc[ai][bj][m][0], v1 = acc[ai][bj][m][1];
; #pragma unroll
;                         for (int j = 0; j < 4; ++j) { v0[j] = gelu_f(v0[j]); v1[j] = gelu_f(v1[j]); }
; #pragma unroll
;                         for (int j = 0; j < 4; ++j) { s += v0[j] + v1[j]; ss += v0[j] * v0[j] + v1[j] * v1[j]; }
;                         *(u32x4*)(GV + (size_t)row * DM + cb + bj * 128) = pack8(v0, v1);
;                     }
;                     s += __shfl_xor(s, 16); s += __shfl_xor(s, 32); ss += __shfl_xor(ss, 16); ss += __shfl_xor(ss, 32);
;                     if (fq == 0) *(f32x2*)(stats + ((size_t)row * 32 + pnv * 4 + wc) * 2) = (f32x2){s, ss};
.LBB0_167:
	s_or_b64 exec, exec, s[72:73]
	v_mul_f32_e32 v147, 0x3d372713, v76
	v_mul_f32_e32 v147, v76, v147
	v_mul_f32_e32 v150, 0x3d372713, v72
	v_fma_f32 v147, v76, v147, v76
	v_mul_f32_e32 v150, v72, v150
	v_mul_f32_e32 v147, 0xc0135761, v147
	v_fma_f32 v150, v72, v150, v72
	v_mul_f32_e32 v150, 0xc0135761, v150
	v_exp_f32_e32 v147, v147
	s_waitcnt lgkmcnt(0)
	v_exp_f32_e32 v153, v150
	v_mul_f32_e32 v174, 0x3d372713, v73
	v_add_f32_e32 v147, 1.0, v147
	v_rcp_f32_e32 v152, v147
	v_add_f32_e32 v147, 1.0, v153
	v_rcp_f32_e32 v153, v147
	v_mul_f32_e32 v174, v73, v174
	v_fma_f32 v174, v73, v174, v73
	v_mul_f32_e32 v174, 0xc0135761, v174
	v_mov_b32_e32 v172, v76
	v_mov_b32_e32 v173, v72
	v_exp_f32_e32 v177, v174
	v_pk_mul_f32 v[174:175], v[172:173], v[152:153]
	v_mul_f32_e32 v180, 0x3d372713, v75
	v_mul_f32_e32 v180, v75, v180
	v_pk_fma_f32 v[152:153], v[172:173], v[152:153], v[174:175] op_sel:[0,0,1] op_sel_hi:[1,1,0]
	v_fma_f32 v180, v75, v180, v75
	v_mul_f32_e32 v153, 0x3d372713, v68
	v_mul_f32_e32 v180, 0xc0135761, v180
	v_mul_f32_e32 v153, v68, v153
	v_fma_f32 v153, v68, v153, v68
	v_exp_f32_e32 v180, v180
	v_mul_f32_e32 v153, 0xc0135761, v153
	v_or_b32_e32 v148, 48, v146
	v_mul_f32_e32 v147, 0x3d372713, v77
	v_ashrrev_i32_e32 v149, 31, v148
	v_mul_f32_e32 v147, v77, v147
	v_exp_f32_e32 v153, v153
	v_lshlrev_b64 v[150:151], 12, v[148:149]
	v_fma_f32 v147, v77, v147, v77
	v_mul_f32_e32 v147, 0xc0135761, v147
	v_add_f32_e32 v180, 1.0, v180
	v_lshl_add_u64 v[150:151], s[10:11], 0, v[150:151]
	v_mul_f32_e32 v172, 0x3d372713, v64
	v_rcp_f32_e32 v183, v180
	v_mul_f32_e32 v172, v64, v172
	v_lshl_add_u64 v[180:181], v[150:151], 0, v[136:137]
	v_mul_f32_e32 v151, 0x3d372713, v69
	v_exp_f32_e32 v147, v147
	v_fma_f32 v172, v64, v172, v64
	v_add_f32_e32 v150, 1.0, v153
	v_mul_f32_e32 v151, v69, v151
	v_mul_f32_e32 v153, 0x3d372713, v65
	v_mul_f32_e32 v172, 0xc0135761, v172
	v_fma_f32 v151, v69, v151, v69
	v_mul_f32_e32 v153, v65, v153
	v_mul_f32_e32 v151, 0xc0135761, v151
	v_fma_f32 v153, v65, v153, v65
	v_exp_f32_e32 v172, v172
	v_mul_f32_e32 v153, 0xc0135761, v153
	v_add_f32_e32 v147, 1.0, v147
	v_exp_f32_e32 v151, v151
	v_rcp_f32_e32 v176, v147
	v_add_f32_e32 v147, 1.0, v177
	v_mul_f32_e32 v177, 0x3d372713, v78
	v_mul_f32_e32 v178, 0x3d372713, v74
	v_exp_f32_e32 v153, v153
	v_mul_f32_e32 v177, v78, v177
	v_mul_f32_e32 v178, v74, v178
	v_fma_f32 v177, v78, v177, v78
	v_fma_f32 v178, v74, v178, v74
	v_rcp_f32_e32 v192, v150
	v_add_f32_e32 v150, 1.0, v172
	v_mul_f32_e32 v177, 0xc0135761, v177
	v_mul_f32_e32 v178, 0xc0135761, v178
	v_rcp_f32_e32 v193, v150
	v_add_f32_e32 v150, 1.0, v151
	v_mul_f32_e32 v151, 0x3d372713, v70
	v_rcp_f32_e32 v194, v150
	v_add_f32_e32 v150, 1.0, v153
	v_mul_f32_e32 v151, v70, v151
	v_mul_f32_e32 v153, 0x3d372713, v66
	v_exp_f32_e32 v177, v177
	v_exp_f32_e32 v179, v178
	v_fma_f32 v151, v70, v151, v70
	v_mul_f32_e32 v153, v66, v153
	v_mul_f32_e32 v151, 0xc0135761, v151
	v_fma_f32 v153, v66, v153, v66
	v_mul_f32_e32 v153, 0xc0135761, v153
	v_exp_f32_e32 v151, v151
	v_rcp_f32_e32 v178, v147
	v_add_f32_e32 v147, 1.0, v177
	v_add_f32_e32 v177, 1.0, v179
	v_mul_f32_e32 v179, 0x3d372713, v79
	v_exp_f32_e32 v153, v153
	v_mul_f32_e32 v179, v79, v179
	v_fma_f32 v179, v79, v179, v79
	v_mul_f32_e32 v179, 0xc0135761, v179
	v_rcp_f32_e32 v195, v150
	v_add_f32_e32 v150, 1.0, v151
	v_mul_f32_e32 v151, 0x3d372713, v71
	v_rcp_f32_e32 v196, v150
	v_add_f32_e32 v150, 1.0, v153
	v_mul_f32_e32 v151, v71, v151
	v_mul_f32_e32 v153, 0x3d372713, v67
	v_exp_f32_e32 v179, v179
	v_fma_f32 v151, v71, v151, v71
	v_mul_f32_e32 v153, v67, v153
	v_mul_f32_e32 v151, 0xc0135761, v151
	v_fma_f32 v153, v67, v153, v67
	v_mul_f32_e32 v153, 0xc0135761, v153
	v_exp_f32_e32 v151, v151
	v_add_f32_e32 v179, 1.0, v179
	v_exp_f32_e32 v153, v153
	v_rcp_f32_e32 v177, v177
	v_rcp_f32_e32 v179, v179
	v_rcp_f32_e32 v197, v150
	v_add_f32_e32 v150, 1.0, v151
	v_rcp_f32_e32 v147, v147
	v_rcp_f32_e32 v198, v150
	v_add_f32_e32 v150, 1.0, v153
	v_rcp_f32_e32 v199, v150
	v_mul_f32_e32 v182, v74, v177
	v_mul_f32_e32 v184, v79, v179
	v_mov_b32_e32 v150, v77
	v_mov_b32_e32 v151, v174
	v_mov_b32_e32 v177, v174
	v_mov_b32_e32 v190, v73
	v_mov_b32_e32 v191, v175
	v_mov_b32_e32 v179, v175
	v_pk_mul_f32 v[188:189], v[150:151], v[176:177]
	v_pk_mul_f32 v[178:179], v[190:191], v[178:179]
	v_mul_f32_e32 v172, v78, v147
	v_pk_fma_f32 v[150:151], v[150:151], v[176:177], v[178:179]
	v_pk_mul_f32 v[176:177], v[188:189], v[188:189]
	v_pk_mul_f32 v[190:191], v[178:179], v[178:179]
	v_mov_b32_e32 v153, v176
	v_mov_b32_e32 v176, v137
	v_mov_b32_e32 v177, v190
	v_mul_f32_e32 v186, v75, v183
	v_pk_add_f32 v[152:153], v[152:153], v[176:177]
	v_mul_f32_e32 v173, v172, v172
	v_mul_f32_e32 v183, v182, v182
	v_pk_add_f32 v[150:151], v[150:151], v[152:153]
	v_pk_add_f32 v[152:153], v[172:173], v[182:183]
	v_mul_f32_e32 v185, v184, v184
	v_mul_f32_e32 v187, v186, v186
	v_pk_add_f32 v[150:151], v[152:153], v[150:151]
	v_pk_add_f32 v[152:153], v[184:185], v[186:187]
	v_mul_f32_e32 v176, v64, v193
	v_pk_add_f32 v[152:153], v[152:153], v[150:151]
	v_cvt_pk_bf16_f32 v150, v174, v188
	v_cvt_pk_bf16_f32 v151, v172, v184
	v_mul_f32_e32 v172, v68, v192
	v_mul_f32_e32 v184, v69, v194
	v_mul_f32_e32 v188, v65, v195
	v_mul_f32_e32 v173, v172, v172
	v_mul_f32_e32 v177, v176, v176
	v_mul_f32_e32 v190, v70, v196
	v_mul_f32_e32 v192, v66, v197
	v_mul_f32_e32 v194, v71, v198
	v_mul_f32_e32 v196, v67, v199
	v_pk_add_f32 v[198:199], v[172:173], v[176:177]
	v_mul_f32_e32 v185, v184, v184
	v_mul_f32_e32 v189, v188, v188
	v_pk_add_f32 v[152:153], v[152:153], v[198:199]
	v_pk_add_f32 v[198:199], v[184:185], v[188:189]
	v_mul_f32_e32 v191, v190, v190
	v_mul_f32_e32 v193, v192, v192
	v_pk_add_f32 v[152:153], v[198:199], v[152:153]
	v_pk_add_f32 v[198:199], v[190:191], v[192:193]
	v_mul_f32_e32 v195, v194, v194
	v_mul_f32_e32 v197, v196, v196
	v_pk_add_f32 v[152:153], v[198:199], v[152:153]
	v_pk_add_f32 v[198:199], v[194:195], v[196:197]
	s_nop 0
	v_pk_add_f32 v[198:199], v[198:199], v[152:153]
	ds_bpermute_b32 v200, v170, v198
	ds_bpermute_b32 v201, v170, v199
	v_cvt_pk_bf16_f32 v152, v175, v178
	v_cvt_pk_bf16_f32 v153, v182, v186
	global_store_dwordx4 v[180:181], v[150:153], off
	v_cvt_pk_bf16_f32 v172, v172, v184
	v_cvt_pk_bf16_f32 v173, v190, v194
	v_cvt_pk_bf16_f32 v174, v176, v188
	v_cvt_pk_bf16_f32 v175, v192, v196
	global_store_dwordx4 v[180:181], v[172:175], off offset:256
	s_waitcnt lgkmcnt(0)
	v_pk_add_f32 v[150:151], v[198:199], v[200:201]
	ds_bpermute_b32 v152, v171, v150
	ds_bpermute_b32 v153, v171, v151
	s_and_saveexec_b64 s[72:73], s[4:5]
	s_cbranch_execz .LBB0_169
	v_lshlrev_b64 v[148:149], 8, v[148:149]
	v_lshl_add_u64 v[148:149], s[16:17], 0, v[148:149]
	s_waitcnt lgkmcnt(0)
	v_pk_add_f32 v[150:151], v[150:151], v[152:153]
	v_lshl_add_u64 v[148:149], s[18:19], 3, v[148:149]
	global_store_dwordx2 v[148:149], v[150:151], off
; __device__ __forceinline__ float gelu_f(float v) { const float u = 1.5957691216057308f * (v + 0.044715f * v * v * v); return v * fast_sigmoid(u); }
; __device__ __forceinline__ u32x4 pack8(const f32x4 a, const f32x4 b) { u32x4 w; w.x = cvt_pk_bf16(a[0], a[1]); w.y = cvt_pk_bf16(a[2], a[3]); w.z = cvt_pk_bf16(b[0], b[1]); w.w = cvt_pk_bf16(b[2], b[3]); return w; }
;     __device__ __forceinline__ void operator()(const Acc& acc, const Unit& u, int wr, int wc, int fr, int fq) const {
;     ...
;             const int pnv = u.pn - 16, cb = pnv * 256 + wc * 32 + 8 * fq;
; #pragma unroll
;             for (int ai = 0; ai < 2; ++ai)
; #pragma unroll
;                 for (int m = 0; m < 4; ++m) {
;                     const int row = u.pm * 256 + ai * 128 + wr * 64 + m * 16 + fr;
;                     float s = 0.f, ss = 0.f;
; #pragma unroll
;                     for (int bj = 0; bj < 2; ++bj) {
;                         f32x4 v0 = acc[ai][bj][m][0], v1 = acc[ai][bj][m][1];
; #pragma unroll
;                         for (int j = 0; j < 4; ++j) { v0[j] = gelu_f(v0[j]); v1[j] = gelu_f(v1[j]); }
; #pragma unroll
;                         for (int j = 0; j < 4; ++j) { s += v0[j] + v1[j]; ss += v0[j] * v0[j] + v1[j] * v1[j]; }
;                         *(u32x4*)(GV + (size_t)row * DM + cb + bj * 128) = pack8(v0, v1);
;                     }
;                     s += __shfl_xor(s, 16); s += __shfl_xor(s, 32); ss += __shfl_xor(ss, 16); ss += __shfl_xor(ss, 32);
;                     if (fq == 0) *(f32x2*)(stats + ((size_t)row * 32 + pnv * 4 + wc) * 2) = (f32x2){s, ss};
.LBB0_169:
	s_or_b64 exec, exec, s[72:73]
	v_mul_f32_e32 v147, 0x3d372713, v60
	v_mul_f32_e32 v147, v60, v147
	v_mul_f32_e32 v150, 0x3d372713, v56
	v_fma_f32 v147, v60, v147, v60
	v_mul_f32_e32 v150, v56, v150
	v_mul_f32_e32 v147, 0xc0135761, v147
	v_fma_f32 v150, v56, v150, v56
	v_mul_f32_e32 v150, 0xc0135761, v150
	v_exp_f32_e32 v147, v147
	s_waitcnt lgkmcnt(0)
	v_exp_f32_e32 v153, v150
	v_mul_f32_e32 v174, 0x3d372713, v57
	v_add_f32_e32 v147, 1.0, v147
	v_rcp_f32_e32 v152, v147
	v_add_f32_e32 v147, 1.0, v153
	v_rcp_f32_e32 v153, v147
	v_mul_f32_e32 v174, v57, v174
	v_fma_f32 v174, v57, v174, v57
	v_mul_f32_e32 v174, 0xc0135761, v174
	v_mov_b32_e32 v172, v60
	v_mov_b32_e32 v173, v56
	v_exp_f32_e32 v177, v174
	v_pk_mul_f32 v[174:175], v[172:173], v[152:153]
	v_mul_f32_e32 v180, 0x3d372713, v59
	v_mul_f32_e32 v180, v59, v180
	v_pk_fma_f32 v[152:153], v[172:173], v[152:153], v[174:175] op_sel:[0,0,1] op_sel_hi:[1,1,0]
	v_fma_f32 v180, v59, v180, v59
	v_mul_f32_e32 v153, 0x3d372713, v52
	v_mul_f32_e32 v180, 0xc0135761, v180
	v_mul_f32_e32 v153, v52, v153
	v_fma_f32 v153, v52, v153, v52
	v_exp_f32_e32 v180, v180
	v_mul_f32_e32 v153, 0xc0135761, v153
	v_add_u32_e32 v148, 0x80, v146
	v_mul_f32_e32 v147, 0x3d372713, v61
	v_ashrrev_i32_e32 v149, 31, v148
	v_mul_f32_e32 v147, v61, v147
	v_exp_f32_e32 v153, v153
	v_lshlrev_b64 v[150:151], 12, v[148:149]
	v_fma_f32 v147, v61, v147, v61
	v_mul_f32_e32 v147, 0xc0135761, v147
	v_add_f32_e32 v180, 1.0, v180
	v_lshl_add_u64 v[150:151], s[10:11], 0, v[150:151]
	v_mul_f32_e32 v172, 0x3d372713, v48
	v_rcp_f32_e32 v183, v180
	v_mul_f32_e32 v172, v48, v172
	v_lshl_add_u64 v[180:181], v[150:151], 0, v[136:137]
	v_mul_f32_e32 v151, 0x3d372713, v53
	v_exp_f32_e32 v147, v147
	v_fma_f32 v172, v48, v172, v48
	v_add_f32_e32 v150, 1.0, v153
	v_mul_f32_e32 v151, v53, v151
	v_mul_f32_e32 v153, 0x3d372713, v49
	v_mul_f32_e32 v172, 0xc0135761, v172
	v_fma_f32 v151, v53, v151, v53
	v_mul_f32_e32 v153, v49, v153
	v_mul_f32_e32 v151, 0xc0135761, v151
	v_fma_f32 v153, v49, v153, v49
	v_exp_f32_e32 v172, v172
	v_mul_f32_e32 v153, 0xc0135761, v153
	v_add_f32_e32 v147, 1.0, v147
	v_exp_f32_e32 v151, v151
	v_rcp_f32_e32 v176, v147
	v_add_f32_e32 v147, 1.0, v177
	v_mul_f32_e32 v177, 0x3d372713, v62
	v_mul_f32_e32 v178, 0x3d372713, v58
	v_exp_f32_e32 v153, v153
	v_mul_f32_e32 v177, v62, v177
	v_mul_f32_e32 v178, v58, v178
	v_fma_f32 v177, v62, v177, v62
	v_fma_f32 v178, v58, v178, v58
	v_rcp_f32_e32 v192, v150
	v_add_f32_e32 v150, 1.0, v172
	v_mul_f32_e32 v177, 0xc0135761, v177
	v_mul_f32_e32 v178, 0xc0135761, v178
	v_rcp_f32_e32 v193, v150
	v_add_f32_e32 v150, 1.0, v151
	v_mul_f32_e32 v151, 0x3d372713, v54
	v_rcp_f32_e32 v194, v150
	v_add_f32_e32 v150, 1.0, v153
	v_mul_f32_e32 v151, v54, v151
	v_mul_f32_e32 v153, 0x3d372713, v50
	v_exp_f32_e32 v177, v177
	v_exp_f32_e32 v179, v178
	v_fma_f32 v151, v54, v151, v54
	v_mul_f32_e32 v153, v50, v153
	v_mul_f32_e32 v151, 0xc0135761, v151
	v_fma_f32 v153, v50, v153, v50
	v_mul_f32_e32 v153, 0xc0135761, v153
	v_exp_f32_e32 v151, v151
	v_rcp_f32_e32 v178, v147
	v_add_f32_e32 v147, 1.0, v177
	v_add_f32_e32 v177, 1.0, v179
	v_mul_f32_e32 v179, 0x3d372713, v63
	v_exp_f32_e32 v153, v153
	v_mul_f32_e32 v179, v63, v179
	v_fma_f32 v179, v63, v179, v63
	v_mul_f32_e32 v179, 0xc0135761, v179
	v_rcp_f32_e32 v195, v150
	v_add_f32_e32 v150, 1.0, v151
	v_mul_f32_e32 v151, 0x3d372713, v55
	v_rcp_f32_e32 v196, v150
	v_add_f32_e32 v150, 1.0, v153
	v_mul_f32_e32 v151, v55, v151
	v_mul_f32_e32 v153, 0x3d372713, v51
	v_exp_f32_e32 v179, v179
	v_fma_f32 v151, v55, v151, v55
	v_mul_f32_e32 v153, v51, v153
	v_mul_f32_e32 v151, 0xc0135761, v151
	v_fma_f32 v153, v51, v153, v51
	v_mul_f32_e32 v153, 0xc0135761, v153
	v_exp_f32_e32 v151, v151
	v_add_f32_e32 v179, 1.0, v179
	v_exp_f32_e32 v153, v153
	v_rcp_f32_e32 v177, v177
	v_rcp_f32_e32 v179, v179
	v_rcp_f32_e32 v197, v150
	v_add_f32_e32 v150, 1.0, v151
	v_rcp_f32_e32 v147, v147
	v_rcp_f32_e32 v198, v150
	v_add_f32_e32 v150, 1.0, v153
	v_rcp_f32_e32 v199, v150
	v_mul_f32_e32 v182, v58, v177
	v_mul_f32_e32 v184, v63, v179
	v_mov_b32_e32 v150, v61
	v_mov_b32_e32 v151, v174
	v_mov_b32_e32 v177, v174
	v_mov_b32_e32 v190, v57
	v_mov_b32_e32 v191, v175
	v_mov_b32_e32 v179, v175
	v_pk_mul_f32 v[188:189], v[150:151], v[176:177]
	v_pk_mul_f32 v[178:179], v[190:191], v[178:179]
	v_mul_f32_e32 v172, v62, v147
	v_pk_fma_f32 v[150:151], v[150:151], v[176:177], v[178:179]
	v_pk_mul_f32 v[176:177], v[188:189], v[188:189]
	v_pk_mul_f32 v[190:191], v[178:179], v[178:179]
	v_mov_b32_e32 v153, v176
	v_mov_b32_e32 v176, v137
	v_mov_b32_e32 v177, v190
	v_mul_f32_e32 v186, v59, v183
	v_pk_add_f32 v[152:153], v[152:153], v[176:177]
	v_mul_f32_e32 v173, v172, v172
	v_mul_f32_e32 v183, v182, v182
	v_pk_add_f32 v[150:151], v[150:151], v[152:153]
	v_pk_add_f32 v[152:153], v[172:173], v[182:183]
	v_mul_f32_e32 v185, v184, v184
	v_mul_f32_e32 v187, v186, v186
	v_pk_add_f32 v[150:151], v[152:153], v[150:151]
	v_pk_add_f32 v[152:153], v[184:185], v[186:187]
	v_mul_f32_e32 v176, v48, v193
	v_pk_add_f32 v[152:153], v[152:153], v[150:151]
	v_cvt_pk_bf16_f32 v150, v174, v188
	v_cvt_pk_bf16_f32 v151, v172, v184
	v_mul_f32_e32 v172, v52, v192
	v_mul_f32_e32 v184, v53, v194
	v_mul_f32_e32 v188, v49, v195
	v_mul_f32_e32 v173, v172, v172
	v_mul_f32_e32 v177, v176, v176
	v_mul_f32_e32 v190, v54, v196
	v_mul_f32_e32 v192, v50, v197
	v_mul_f32_e32 v194, v55, v198
	v_mul_f32_e32 v196, v51, v199
	v_pk_add_f32 v[198:199], v[172:173], v[176:177]
	v_mul_f32_e32 v185, v184, v184
	v_mul_f32_e32 v189, v188, v188
	v_pk_add_f32 v[152:153], v[152:153], v[198:199]
	v_pk_add_f32 v[198:199], v[184:185], v[188:189]
	v_mul_f32_e32 v191, v190, v190
	v_mul_f32_e32 v193, v192, v192
	v_pk_add_f32 v[152:153], v[198:199], v[152:153]
	v_pk_add_f32 v[198:199], v[190:191], v[192:193]
	v_mul_f32_e32 v195, v194, v194
	v_mul_f32_e32 v197, v196, v196
	v_pk_add_f32 v[152:153], v[198:199], v[152:153]
	v_pk_add_f32 v[198:199], v[194:195], v[196:197]
	s_nop 0
	v_pk_add_f32 v[198:199], v[198:199], v[152:153]
	ds_bpermute_b32 v200, v170, v198
	ds_bpermute_b32 v201, v170, v199
	v_cvt_pk_bf16_f32 v152, v175, v178
	v_cvt_pk_bf16_f32 v153, v182, v186
	global_store_dwordx4 v[180:181], v[150:153], off
	v_cvt_pk_bf16_f32 v172, v172, v184
	v_cvt_pk_bf16_f32 v173, v190, v194
	v_cvt_pk_bf16_f32 v174, v176, v188
	v_cvt_pk_bf16_f32 v175, v192, v196
	global_store_dwordx4 v[180:181], v[172:175], off offset:256
	s_waitcnt lgkmcnt(0)
	v_pk_add_f32 v[150:151], v[198:199], v[200:201]
	ds_bpermute_b32 v152, v171, v150
	ds_bpermute_b32 v153, v171, v151
	s_and_saveexec_b64 s[72:73], s[4:5]
	s_cbranch_execz .LBB0_171
	v_lshlrev_b64 v[148:149], 8, v[148:149]
	v_lshl_add_u64 v[148:149], s[16:17], 0, v[148:149]
	s_waitcnt lgkmcnt(0)
	v_pk_add_f32 v[150:151], v[150:151], v[152:153]
	v_lshl_add_u64 v[148:149], s[18:19], 3, v[148:149]
	global_store_dwordx2 v[148:149], v[150:151], off
; __device__ __forceinline__ float gelu_f(float v) { const float u = 1.5957691216057308f * (v + 0.044715f * v * v * v); return v * fast_sigmoid(u); }
; __device__ __forceinline__ u32x4 pack8(const f32x4 a, const f32x4 b) { u32x4 w; w.x = cvt_pk_bf16(a[0], a[1]); w.y = cvt_pk_bf16(a[2], a[3]); w.z = cvt_pk_bf16(b[0], b[1]); w.w = cvt_pk_bf16(b[2], b[3]); return w; }
;     __device__ __forceinline__ void operator()(const Acc& acc, const Unit& u, int wr, int wc, int fr, int fq) const {
;     ...
;             const int pnv = u.pn - 16, cb = pnv * 256 + wc * 32 + 8 * fq;
; #pragma unroll
;             for (int ai = 0; ai < 2; ++ai)
; #pragma unroll
;                 for (int m = 0; m < 4; ++m) {
;                     const int row = u.pm * 256 + ai * 128 + wr * 64 + m * 16 + fr;
;                     float s = 0.f, ss = 0.f;
; #pragma unroll
;                     for (int bj = 0; bj < 2; ++bj) {
;                         f32x4 v0 = acc[ai][bj][m][0], v1 = acc[ai][bj][m][1];
; #pragma unroll
;                         for (int j = 0; j < 4; ++j) { v0[j] = gelu_f(v0[j]); v1[j] = gelu_f(v1[j]); }
; #pragma unroll
;                         for (int j = 0; j < 4; ++j) { s += v0[j] + v1[j]; ss += v0[j] * v0[j] + v1[j] * v1[j]; }
;                         *(u32x4*)(GV + (size_t)row * DM + cb + bj * 128) = pack8(v0, v1);
;                     }
;                     s += __shfl_xor(s, 16); s += __shfl_xor(s, 32); ss += __shfl_xor(ss, 16); ss += __shfl_xor(ss, 32);
;                     if (fq == 0) *(f32x2*)(stats + ((size_t)row * 32 + pnv * 4 + wc) * 2) = (f32x2){s, ss};
.LBB0_171:
	s_or_b64 exec, exec, s[72:73]
	v_mul_f32_e32 v147, 0x3d372713, v44
	v_mul_f32_e32 v147, v44, v147
	v_mul_f32_e32 v150, 0x3d372713, v40
	v_fma_f32 v147, v44, v147, v44
	v_mul_f32_e32 v150, v40, v150
	v_mul_f32_e32 v147, 0xc0135761, v147
	v_fma_f32 v150, v40, v150, v40
	v_mul_f32_e32 v150, 0xc0135761, v150
	v_exp_f32_e32 v147, v147
	s_waitcnt lgkmcnt(0)
	v_exp_f32_e32 v153, v150
	v_mul_f32_e32 v174, 0x3d372713, v41
	v_add_f32_e32 v147, 1.0, v147
	v_rcp_f32_e32 v152, v147
	v_add_f32_e32 v147, 1.0, v153
	v_rcp_f32_e32 v153, v147
	v_mul_f32_e32 v174, v41, v174
	v_fma_f32 v174, v41, v174, v41
	v_mul_f32_e32 v174, 0xc0135761, v174
	v_mov_b32_e32 v172, v44
	v_mov_b32_e32 v173, v40
	v_exp_f32_e32 v177, v174
	v_pk_mul_f32 v[174:175], v[172:173], v[152:153]
	v_mul_f32_e32 v180, 0x3d372713, v43
	v_mul_f32_e32 v180, v43, v180
	v_pk_fma_f32 v[152:153], v[172:173], v[152:153], v[174:175] op_sel:[0,0,1] op_sel_hi:[1,1,0]
	v_fma_f32 v180, v43, v180, v43
	v_mul_f32_e32 v153, 0x3d372713, v36
	v_mul_f32_e32 v180, 0xc0135761, v180
	v_mul_f32_e32 v153, v36, v153
	v_fma_f32 v153, v36, v153, v36
	v_exp_f32_e32 v180, v180
	v_mul_f32_e32 v153, 0xc0135761, v153
	v_add_u32_e32 v148, 0x90, v146
	v_mul_f32_e32 v147, 0x3d372713, v45
	v_ashrrev_i32_e32 v149, 31, v148
	v_mul_f32_e32 v147, v45, v147
	v_exp_f32_e32 v153, v153
	v_lshlrev_b64 v[150:151], 12, v[148:149]
	v_fma_f32 v147, v45, v147, v45
	v_mul_f32_e32 v147, 0xc0135761, v147
	v_add_f32_e32 v180, 1.0, v180
	v_lshl_add_u64 v[150:151], s[10:11], 0, v[150:151]
	v_mul_f32_e32 v172, 0x3d372713, v32
	v_rcp_f32_e32 v183, v180
	v_mul_f32_e32 v172, v32, v172
	v_lshl_add_u64 v[180:181], v[150:151], 0, v[136:137]
	v_mul_f32_e32 v151, 0x3d372713, v37
	v_exp_f32_e32 v147, v147
	v_fma_f32 v172, v32, v172, v32
	v_add_f32_e32 v150, 1.0, v153
	v_mul_f32_e32 v151, v37, v151
	v_mul_f32_e32 v153, 0x3d372713, v33
	v_mul_f32_e32 v172, 0xc0135761, v172
	v_fma_f32 v151, v37, v151, v37
	v_mul_f32_e32 v153, v33, v153
	v_mul_f32_e32 v151, 0xc0135761, v151
	v_fma_f32 v153, v33, v153, v33
	v_exp_f32_e32 v172, v172
	v_mul_f32_e32 v153, 0xc0135761, v153
	v_add_f32_e32 v147, 1.0, v147
	v_exp_f32_e32 v151, v151
	v_rcp_f32_e32 v176, v147
	v_add_f32_e32 v147, 1.0, v177
	v_mul_f32_e32 v177, 0x3d372713, v46
	v_mul_f32_e32 v178, 0x3d372713, v42
	v_exp_f32_e32 v153, v153
	v_mul_f32_e32 v177, v46, v177
	v_mul_f32_e32 v178, v42, v178
	v_fma_f32 v177, v46, v177, v46
	v_fma_f32 v178, v42, v178, v42
	v_rcp_f32_e32 v192, v150
	v_add_f32_e32 v150, 1.0, v172
	v_mul_f32_e32 v177, 0xc0135761, v177
	v_mul_f32_e32 v178, 0xc0135761, v178
	v_rcp_f32_e32 v193, v150
	v_add_f32_e32 v150, 1.0, v151
	v_mul_f32_e32 v151, 0x3d372713, v38
	v_rcp_f32_e32 v194, v150
	v_add_f32_e32 v150, 1.0, v153
	v_mul_f32_e32 v151, v38, v151
	v_mul_f32_e32 v153, 0x3d372713, v34
	v_exp_f32_e32 v177, v177
	v_exp_f32_e32 v179, v178
	v_fma_f32 v151, v38, v151, v38
	v_mul_f32_e32 v153, v34, v153
	v_mul_f32_e32 v151, 0xc0135761, v151
	v_fma_f32 v153, v34, v153, v34
	v_mul_f32_e32 v153, 0xc0135761, v153
	v_exp_f32_e32 v151, v151
	v_rcp_f32_e32 v178, v147
	v_add_f32_e32 v147, 1.0, v177
	v_add_f32_e32 v177, 1.0, v179
	v_mul_f32_e32 v179, 0x3d372713, v47
	v_exp_f32_e32 v153, v153
	v_mul_f32_e32 v179, v47, v179
	v_fma_f32 v179, v47, v179, v47
	v_mul_f32_e32 v179, 0xc0135761, v179
	v_rcp_f32_e32 v195, v150
	v_add_f32_e32 v150, 1.0, v151
	v_mul_f32_e32 v151, 0x3d372713, v39
	v_rcp_f32_e32 v196, v150
	v_add_f32_e32 v150, 1.0, v153
	v_mul_f32_e32 v151, v39, v151
	v_mul_f32_e32 v153, 0x3d372713, v35
	v_exp_f32_e32 v179, v179
	v_fma_f32 v151, v39, v151, v39
	v_mul_f32_e32 v153, v35, v153
	v_mul_f32_e32 v151, 0xc0135761, v151
	v_fma_f32 v153, v35, v153, v35
	v_mul_f32_e32 v153, 0xc0135761, v153
	v_exp_f32_e32 v151, v151
	v_add_f32_e32 v179, 1.0, v179
	v_exp_f32_e32 v153, v153
	v_rcp_f32_e32 v177, v177
	v_rcp_f32_e32 v179, v179
	v_rcp_f32_e32 v197, v150
	v_add_f32_e32 v150, 1.0, v151
	v_rcp_f32_e32 v147, v147
	v_rcp_f32_e32 v198, v150
	v_add_f32_e32 v150, 1.0, v153
	v_rcp_f32_e32 v199, v150
	v_mul_f32_e32 v182, v42, v177
	v_mul_f32_e32 v184, v47, v179
	v_mov_b32_e32 v150, v45
	v_mov_b32_e32 v151, v174
	v_mov_b32_e32 v177, v174
	v_mov_b32_e32 v190, v41
	v_mov_b32_e32 v191, v175
	v_mov_b32_e32 v179, v175
	v_pk_mul_f32 v[188:189], v[150:151], v[176:177]
	v_pk_mul_f32 v[178:179], v[190:191], v[178:179]
	v_mul_f32_e32 v172, v46, v147
	v_pk_fma_f32 v[150:151], v[150:151], v[176:177], v[178:179]
	v_pk_mul_f32 v[176:177], v[188:189], v[188:189]
	v_pk_mul_f32 v[190:191], v[178:179], v[178:179]
	v_mov_b32_e32 v153, v176
	v_mov_b32_e32 v176, v137
	v_mov_b32_e32 v177, v190
	v_mul_f32_e32 v186, v43, v183
	v_pk_add_f32 v[152:153], v[152:153], v[176:177]
	v_mul_f32_e32 v173, v172, v172
	v_mul_f32_e32 v183, v182, v182
	v_pk_add_f32 v[150:151], v[150:151], v[152:153]
	v_pk_add_f32 v[152:153], v[172:173], v[182:183]
	v_mul_f32_e32 v185, v184, v184
	v_mul_f32_e32 v187, v186, v186
	v_pk_add_f32 v[150:151], v[152:153], v[150:151]
	v_pk_add_f32 v[152:153], v[184:185], v[186:187]
	v_mul_f32_e32 v176, v32, v193
	v_pk_add_f32 v[152:153], v[152:153], v[150:151]
	v_cvt_pk_bf16_f32 v150, v174, v188
	v_cvt_pk_bf16_f32 v151, v172, v184
	v_mul_f32_e32 v172, v36, v192
	v_mul_f32_e32 v184, v37, v194
	v_mul_f32_e32 v188, v33, v195
	v_mul_f32_e32 v173, v172, v172
	v_mul_f32_e32 v177, v176, v176
	v_mul_f32_e32 v190, v38, v196
	v_mul_f32_e32 v192, v34, v197
	v_mul_f32_e32 v194, v39, v198
	v_mul_f32_e32 v196, v35, v199
	v_pk_add_f32 v[198:199], v[172:173], v[176:177]
	v_mul_f32_e32 v185, v184, v184
	v_mul_f32_e32 v189, v188, v188
	v_pk_add_f32 v[152:153], v[152:153], v[198:199]
	v_pk_add_f32 v[198:199], v[184:185], v[188:189]
	v_mul_f32_e32 v191, v190, v190
	v_mul_f32_e32 v193, v192, v192
	v_pk_add_f32 v[152:153], v[198:199], v[152:153]
	v_pk_add_f32 v[198:199], v[190:191], v[192:193]
	v_mul_f32_e32 v195, v194, v194
	v_mul_f32_e32 v197, v196, v196
	v_pk_add_f32 v[152:153], v[198:199], v[152:153]
	v_pk_add_f32 v[198:199], v[194:195], v[196:197]
	s_nop 0
	v_pk_add_f32 v[198:199], v[198:199], v[152:153]
	ds_bpermute_b32 v200, v170, v198
	ds_bpermute_b32 v201, v170, v199
	v_cvt_pk_bf16_f32 v152, v175, v178
	v_cvt_pk_bf16_f32 v153, v182, v186
	global_store_dwordx4 v[180:181], v[150:153], off
	v_cvt_pk_bf16_f32 v172, v172, v184
	v_cvt_pk_bf16_f32 v173, v190, v194
	v_cvt_pk_bf16_f32 v174, v176, v188
	v_cvt_pk_bf16_f32 v175, v192, v196
	global_store_dwordx4 v[180:181], v[172:175], off offset:256
	s_waitcnt lgkmcnt(0)
	v_pk_add_f32 v[150:151], v[198:199], v[200:201]
	ds_bpermute_b32 v152, v171, v150
	ds_bpermute_b32 v153, v171, v151
	s_and_saveexec_b64 s[72:73], s[4:5]
	s_cbranch_execz .LBB0_173
	v_lshlrev_b64 v[148:149], 8, v[148:149]
	v_lshl_add_u64 v[148:149], s[16:17], 0, v[148:149]
	s_waitcnt lgkmcnt(0)
	v_pk_add_f32 v[150:151], v[150:151], v[152:153]
	v_lshl_add_u64 v[148:149], s[18:19], 3, v[148:149]
	global_store_dwordx2 v[148:149], v[150:151], off
; __device__ __forceinline__ float gelu_f(float v) { const float u = 1.5957691216057308f * (v + 0.044715f * v * v * v); return v * fast_sigmoid(u); }
; __device__ __forceinline__ u32x4 pack8(const f32x4 a, const f32x4 b) { u32x4 w; w.x = cvt_pk_bf16(a[0], a[1]); w.y = cvt_pk_bf16(a[2], a[3]); w.z = cvt_pk_bf16(b[0], b[1]); w.w = cvt_pk_bf16(b[2], b[3]); return w; }
;     __device__ __forceinline__ void operator()(const Acc& acc, const Unit& u, int wr, int wc, int fr, int fq) const {
;     ...
;             const int pnv = u.pn - 16, cb = pnv * 256 + wc * 32 + 8 * fq;
; #pragma unroll
;             for (int ai = 0; ai < 2; ++ai)
; #pragma unroll
;                 for (int m = 0; m < 4; ++m) {
;                     const int row = u.pm * 256 + ai * 128 + wr * 64 + m * 16 + fr;
;                     float s = 0.f, ss = 0.f;
; #pragma unroll
;                     for (int bj = 0; bj < 2; ++bj) {
;                         f32x4 v0 = acc[ai][bj][m][0], v1 = acc[ai][bj][m][1];
; #pragma unroll
;                         for (int j = 0; j < 4; ++j) { v0[j] = gelu_f(v0[j]); v1[j] = gelu_f(v1[j]); }
; #pragma unroll
;                         for (int j = 0; j < 4; ++j) { s += v0[j] + v1[j]; ss += v0[j] * v0[j] + v1[j] * v1[j]; }
;                         *(u32x4*)(GV + (size_t)row * DM + cb + bj * 128) = pack8(v0, v1);
;                     }
;                     s += __shfl_xor(s, 16); s += __shfl_xor(s, 32); ss += __shfl_xor(ss, 16); ss += __shfl_xor(ss, 32);
;                     if (fq == 0) *(f32x2*)(stats + ((size_t)row * 32 + pnv * 4 + wc) * 2) = (f32x2){s, ss};
.LBB0_173:
	s_or_b64 exec, exec, s[72:73]
	v_mul_f32_e32 v147, 0x3d372713, v28
	v_mul_f32_e32 v147, v28, v147
	v_mul_f32_e32 v150, 0x3d372713, v24
	v_fma_f32 v147, v28, v147, v28
	v_mul_f32_e32 v150, v24, v150
	v_mul_f32_e32 v147, 0xc0135761, v147
	v_fma_f32 v150, v24, v150, v24
	v_mul_f32_e32 v150, 0xc0135761, v150
	v_exp_f32_e32 v147, v147
	s_waitcnt lgkmcnt(0)
	v_exp_f32_e32 v153, v150
	v_mul_f32_e32 v174, 0x3d372713, v25
	v_add_f32_e32 v147, 1.0, v147
	v_rcp_f32_e32 v152, v147
	v_add_f32_e32 v147, 1.0, v153
	v_rcp_f32_e32 v153, v147
	v_mul_f32_e32 v174, v25, v174
	v_fma_f32 v174, v25, v174, v25
	v_mul_f32_e32 v174, 0xc0135761, v174
	v_mov_b32_e32 v172, v28
	v_mov_b32_e32 v173, v24
	v_exp_f32_e32 v177, v174
	v_pk_mul_f32 v[174:175], v[172:173], v[152:153]
	v_mul_f32_e32 v180, 0x3d372713, v27
	v_mul_f32_e32 v180, v27, v180
	v_pk_fma_f32 v[152:153], v[172:173], v[152:153], v[174:175] op_sel:[0,0,1] op_sel_hi:[1,1,0]
	v_fma_f32 v180, v27, v180, v27
	v_mul_f32_e32 v153, 0x3d372713, v20
	v_mul_f32_e32 v180, 0xc0135761, v180
	v_mul_f32_e32 v153, v20, v153
	v_fma_f32 v153, v20, v153, v20
	v_exp_f32_e32 v180, v180
	v_mul_f32_e32 v153, 0xc0135761, v153
	v_add_u32_e32 v148, 0xa0, v146
	v_mul_f32_e32 v147, 0x3d372713, v29
	v_ashrrev_i32_e32 v149, 31, v148
	v_mul_f32_e32 v147, v29, v147
	v_exp_f32_e32 v153, v153
	v_lshlrev_b64 v[150:151], 12, v[148:149]
	v_fma_f32 v147, v29, v147, v29
	v_mul_f32_e32 v147, 0xc0135761, v147
	v_add_f32_e32 v180, 1.0, v180
	v_lshl_add_u64 v[150:151], s[10:11], 0, v[150:151]
	v_mul_f32_e32 v172, 0x3d372713, v16
	v_rcp_f32_e32 v183, v180
	v_mul_f32_e32 v172, v16, v172
	v_lshl_add_u64 v[180:181], v[150:151], 0, v[136:137]
	v_mul_f32_e32 v151, 0x3d372713, v21
	v_exp_f32_e32 v147, v147
	v_fma_f32 v172, v16, v172, v16
	v_add_f32_e32 v150, 1.0, v153
	v_mul_f32_e32 v151, v21, v151
	v_mul_f32_e32 v153, 0x3d372713, v17
	v_mul_f32_e32 v172, 0xc0135761, v172
	v_fma_f32 v151, v21, v151, v21
	v_mul_f32_e32 v153, v17, v153
	v_mul_f32_e32 v151, 0xc0135761, v151
	v_fma_f32 v153, v17, v153, v17
	v_exp_f32_e32 v172, v172
	v_mul_f32_e32 v153, 0xc0135761, v153
	v_add_f32_e32 v147, 1.0, v147
	v_exp_f32_e32 v151, v151
	v_rcp_f32_e32 v176, v147
	v_add_f32_e32 v147, 1.0, v177
	v_mul_f32_e32 v177, 0x3d372713, v30
	v_mul_f32_e32 v178, 0x3d372713, v26
	v_exp_f32_e32 v153, v153
	v_mul_f32_e32 v177, v30, v177
	v_mul_f32_e32 v178, v26, v178
	v_fma_f32 v177, v30, v177, v30
	v_fma_f32 v178, v26, v178, v26
	v_rcp_f32_e32 v192, v150
	v_add_f32_e32 v150, 1.0, v172
	v_mul_f32_e32 v177, 0xc0135761, v177
	v_mul_f32_e32 v178, 0xc0135761, v178
	v_rcp_f32_e32 v193, v150
	v_add_f32_e32 v150, 1.0, v151
	v_mul_f32_e32 v151, 0x3d372713, v22
	v_rcp_f32_e32 v194, v150
	v_add_f32_e32 v150, 1.0, v153
	v_mul_f32_e32 v151, v22, v151
	v_mul_f32_e32 v153, 0x3d372713, v18
	v_exp_f32_e32 v177, v177
	v_exp_f32_e32 v179, v178
	v_fma_f32 v151, v22, v151, v22
	v_mul_f32_e32 v153, v18, v153
	v_mul_f32_e32 v151, 0xc0135761, v151
	v_fma_f32 v153, v18, v153, v18
	v_mul_f32_e32 v153, 0xc0135761, v153
	v_exp_f32_e32 v151, v151
	v_rcp_f32_e32 v178, v147
	v_add_f32_e32 v147, 1.0, v177
	v_add_f32_e32 v177, 1.0, v179
	v_mul_f32_e32 v179, 0x3d372713, v31
	v_exp_f32_e32 v153, v153
	v_mul_f32_e32 v179, v31, v179
	v_fma_f32 v179, v31, v179, v31
	v_mul_f32_e32 v179, 0xc0135761, v179
	v_rcp_f32_e32 v195, v150
	v_add_f32_e32 v150, 1.0, v151
	v_mul_f32_e32 v151, 0x3d372713, v23
	v_rcp_f32_e32 v196, v150
	v_add_f32_e32 v150, 1.0, v153
	v_mul_f32_e32 v151, v23, v151
	v_mul_f32_e32 v153, 0x3d372713, v19
	v_exp_f32_e32 v179, v179
	v_fma_f32 v151, v23, v151, v23
	v_mul_f32_e32 v153, v19, v153
	v_mul_f32_e32 v151, 0xc0135761, v151
	v_fma_f32 v153, v19, v153, v19
	v_mul_f32_e32 v153, 0xc0135761, v153
	v_exp_f32_e32 v151, v151
	v_add_f32_e32 v179, 1.0, v179
	v_exp_f32_e32 v153, v153
	v_rcp_f32_e32 v177, v177
	v_rcp_f32_e32 v179, v179
	v_rcp_f32_e32 v197, v150
	v_add_f32_e32 v150, 1.0, v151
	v_rcp_f32_e32 v147, v147
	v_rcp_f32_e32 v198, v150
	v_add_f32_e32 v150, 1.0, v153
	v_rcp_f32_e32 v199, v150
	v_mul_f32_e32 v182, v26, v177
	v_mul_f32_e32 v184, v31, v179
	v_mov_b32_e32 v150, v29
	v_mov_b32_e32 v151, v174
	v_mov_b32_e32 v177, v174
	v_mov_b32_e32 v190, v25
	v_mov_b32_e32 v191, v175
	v_mov_b32_e32 v179, v175
	v_pk_mul_f32 v[188:189], v[150:151], v[176:177]
	v_pk_mul_f32 v[178:179], v[190:191], v[178:179]
	v_mul_f32_e32 v172, v30, v147
	v_pk_fma_f32 v[150:151], v[150:151], v[176:177], v[178:179]
	v_pk_mul_f32 v[176:177], v[188:189], v[188:189]
	v_pk_mul_f32 v[190:191], v[178:179], v[178:179]
	v_mov_b32_e32 v153, v176
	v_mov_b32_e32 v176, v137
	v_mov_b32_e32 v177, v190
	v_mul_f32_e32 v186, v27, v183
	v_pk_add_f32 v[152:153], v[152:153], v[176:177]
	v_mul_f32_e32 v173, v172, v172
	v_mul_f32_e32 v183, v182, v182
	v_pk_add_f32 v[150:151], v[150:151], v[152:153]
	v_pk_add_f32 v[152:153], v[172:173], v[182:183]
	v_mul_f32_e32 v185, v184, v184
	v_mul_f32_e32 v187, v186, v186
	v_pk_add_f32 v[150:151], v[152:153], v[150:151]
	v_pk_add_f32 v[152:153], v[184:185], v[186:187]
	v_mul_f32_e32 v176, v16, v193
	v_pk_add_f32 v[152:153], v[152:153], v[150:151]
	v_cvt_pk_bf16_f32 v150, v174, v188
	v_cvt_pk_bf16_f32 v151, v172, v184
	v_mul_f32_e32 v172, v20, v192
	v_mul_f32_e32 v184, v21, v194
	v_mul_f32_e32 v188, v17, v195
	v_mul_f32_e32 v173, v172, v172
	v_mul_f32_e32 v177, v176, v176
	v_mul_f32_e32 v190, v22, v196
	v_mul_f32_e32 v192, v18, v197
	v_mul_f32_e32 v194, v23, v198
	v_mul_f32_e32 v196, v19, v199
	v_pk_add_f32 v[198:199], v[172:173], v[176:177]
	v_mul_f32_e32 v185, v184, v184
	v_mul_f32_e32 v189, v188, v188
	v_pk_add_f32 v[152:153], v[152:153], v[198:199]
	v_pk_add_f32 v[198:199], v[184:185], v[188:189]
	v_mul_f32_e32 v191, v190, v190
	v_mul_f32_e32 v193, v192, v192
	v_pk_add_f32 v[152:153], v[198:199], v[152:153]
	v_pk_add_f32 v[198:199], v[190:191], v[192:193]
	v_mul_f32_e32 v195, v194, v194
	v_mul_f32_e32 v197, v196, v196
	v_pk_add_f32 v[152:153], v[198:199], v[152:153]
	v_pk_add_f32 v[198:199], v[194:195], v[196:197]
	s_nop 0
	v_pk_add_f32 v[198:199], v[198:199], v[152:153]
	ds_bpermute_b32 v200, v170, v198
	ds_bpermute_b32 v201, v170, v199
	v_cvt_pk_bf16_f32 v152, v175, v178
	v_cvt_pk_bf16_f32 v153, v182, v186
	global_store_dwordx4 v[180:181], v[150:153], off
	v_cvt_pk_bf16_f32 v172, v172, v184
	v_cvt_pk_bf16_f32 v173, v190, v194
	v_cvt_pk_bf16_f32 v174, v176, v188
	v_cvt_pk_bf16_f32 v175, v192, v196
	global_store_dwordx4 v[180:181], v[172:175], off offset:256
	s_waitcnt lgkmcnt(0)
	v_pk_add_f32 v[150:151], v[198:199], v[200:201]
	ds_bpermute_b32 v152, v171, v150
	ds_bpermute_b32 v153, v171, v151
	s_and_saveexec_b64 s[72:73], s[4:5]
	s_cbranch_execz .LBB0_175
	v_lshlrev_b64 v[148:149], 8, v[148:149]
	v_lshl_add_u64 v[148:149], s[16:17], 0, v[148:149]
	s_waitcnt lgkmcnt(0)
	v_pk_add_f32 v[150:151], v[150:151], v[152:153]
	v_lshl_add_u64 v[148:149], s[18:19], 3, v[148:149]
	global_store_dwordx2 v[148:149], v[150:151], off
; __device__ __forceinline__ float gelu_f(float v) { const float u = 1.5957691216057308f * (v + 0.044715f * v * v * v); return v * fast_sigmoid(u); }
; __device__ __forceinline__ u32x4 pack8(const f32x4 a, const f32x4 b) { u32x4 w; w.x = cvt_pk_bf16(a[0], a[1]); w.y = cvt_pk_bf16(a[2], a[3]); w.z = cvt_pk_bf16(b[0], b[1]); w.w = cvt_pk_bf16(b[2], b[3]); return w; }
;     __device__ __forceinline__ void operator()(const Acc& acc, const Unit& u, int wr, int wc, int fr, int fq) const {
;     ...
;             const int pnv = u.pn - 16, cb = pnv * 256 + wc * 32 + 8 * fq;
; #pragma unroll
;             for (int ai = 0; ai < 2; ++ai)
; #pragma unroll
;                 for (int m = 0; m < 4; ++m) {
;                     const int row = u.pm * 256 + ai * 128 + wr * 64 + m * 16 + fr;
;                     float s = 0.f, ss = 0.f;
; #pragma unroll
;                     for (int bj = 0; bj < 2; ++bj) {
;                         f32x4 v0 = acc[ai][bj][m][0], v1 = acc[ai][bj][m][1];
; #pragma unroll
;                         for (int j = 0; j < 4; ++j) { v0[j] = gelu_f(v0[j]); v1[j] = gelu_f(v1[j]); }
; #pragma unroll
;                         for (int j = 0; j < 4; ++j) { s += v0[j] + v1[j]; ss += v0[j] * v0[j] + v1[j] * v1[j]; }
;                         *(u32x4*)(GV + (size_t)row * DM + cb + bj * 128) = pack8(v0, v1);
;                     }
;                     s += __shfl_xor(s, 16); s += __shfl_xor(s, 32); ss += __shfl_xor(ss, 16); ss += __shfl_xor(ss, 32);
;                     if (fq == 0) *(f32x2*)(stats + ((size_t)row * 32 + pnv * 4 + wc) * 2) = (f32x2){s, ss};
.LBB0_175:
	s_or_b64 exec, exec, s[72:73]
	v_mul_f32_e32 v147, 0x3d372713, v12
	v_mul_f32_e32 v147, v12, v147
	v_mul_f32_e32 v150, 0x3d372713, v8
	v_fma_f32 v147, v12, v147, v12
	v_mul_f32_e32 v150, v8, v150
	v_mul_f32_e32 v147, 0xc0135761, v147
	v_fma_f32 v150, v8, v150, v8
	v_mul_f32_e32 v150, 0xc0135761, v150
	v_exp_f32_e32 v147, v147
	s_waitcnt lgkmcnt(0)
	v_exp_f32_e32 v153, v150
	v_mul_f32_e32 v174, 0x3d372713, v9
	v_add_f32_e32 v147, 1.0, v147
	v_rcp_f32_e32 v152, v147
	v_add_f32_e32 v147, 1.0, v153
	v_rcp_f32_e32 v153, v147
	v_mul_f32_e32 v174, v9, v174
	v_fma_f32 v174, v9, v174, v9
	v_mul_f32_e32 v174, 0xc0135761, v174
	v_mov_b32_e32 v172, v12
	v_mov_b32_e32 v173, v8
	v_exp_f32_e32 v177, v174
	v_pk_mul_f32 v[174:175], v[172:173], v[152:153]
	v_mul_f32_e32 v180, 0x3d372713, v11
	v_mul_f32_e32 v180, v11, v180
	v_pk_fma_f32 v[152:153], v[172:173], v[152:153], v[174:175] op_sel:[0,0,1] op_sel_hi:[1,1,0]
	v_fma_f32 v180, v11, v180, v11
	v_mul_f32_e32 v153, 0x3d372713, v4
	v_mul_f32_e32 v180, 0xc0135761, v180
	v_mul_f32_e32 v153, v4, v153
	v_fma_f32 v153, v4, v153, v4
	v_exp_f32_e32 v180, v180
	v_mul_f32_e32 v153, 0xc0135761, v153
	v_add_u32_e32 v148, 0xb0, v146
	v_mul_f32_e32 v147, 0x3d372713, v13
	v_ashrrev_i32_e32 v149, 31, v148
	v_mul_f32_e32 v147, v13, v147
	v_exp_f32_e32 v153, v153
	v_lshlrev_b64 v[150:151], 12, v[148:149]
	v_fma_f32 v147, v13, v147, v13
	v_mul_f32_e32 v147, 0xc0135761, v147
	v_add_f32_e32 v180, 1.0, v180
	v_lshl_add_u64 v[150:151], s[10:11], 0, v[150:151]
	v_mul_f32_e32 v172, 0x3d372713, v0
	v_rcp_f32_e32 v183, v180
	v_mul_f32_e32 v172, v0, v172
	v_lshl_add_u64 v[180:181], v[150:151], 0, v[136:137]
	v_mul_f32_e32 v151, 0x3d372713, v5
	v_exp_f32_e32 v147, v147
	v_fma_f32 v172, v0, v172, v0
	v_add_f32_e32 v136, 1.0, v153
	v_mul_f32_e32 v151, v5, v151
	v_mul_f32_e32 v153, 0x3d372713, v1
	v_mul_f32_e32 v172, 0xc0135761, v172
	v_fma_f32 v151, v5, v151, v5
	v_mul_f32_e32 v153, v1, v153
	v_mul_f32_e32 v151, 0xc0135761, v151
	v_fma_f32 v153, v1, v153, v1
	v_exp_f32_e32 v172, v172
	v_mul_f32_e32 v153, 0xc0135761, v153
	v_add_f32_e32 v147, 1.0, v147
	v_exp_f32_e32 v151, v151
	v_rcp_f32_e32 v176, v147
	v_add_f32_e32 v147, 1.0, v177
	v_mul_f32_e32 v177, 0x3d372713, v14
	v_mul_f32_e32 v178, 0x3d372713, v10
	v_exp_f32_e32 v153, v153
	v_mul_f32_e32 v177, v14, v177
	v_mul_f32_e32 v178, v10, v178
	v_fma_f32 v177, v14, v177, v14
	v_fma_f32 v178, v10, v178, v10
	v_add_f32_e32 v150, 1.0, v172
	v_mul_f32_e32 v177, 0xc0135761, v177
	v_mul_f32_e32 v178, 0xc0135761, v178
	v_rcp_f32_e32 v192, v150
	v_add_f32_e32 v150, 1.0, v151
	v_mul_f32_e32 v151, 0x3d372713, v6
	v_rcp_f32_e32 v193, v150
	v_add_f32_e32 v150, 1.0, v153
	v_mul_f32_e32 v151, v6, v151
	v_mul_f32_e32 v153, 0x3d372713, v2
	v_exp_f32_e32 v177, v177
	v_exp_f32_e32 v179, v178
	v_fma_f32 v151, v6, v151, v6
	v_mul_f32_e32 v153, v2, v153
	v_mul_f32_e32 v151, 0xc0135761, v151
	v_fma_f32 v153, v2, v153, v2
	v_mul_f32_e32 v153, 0xc0135761, v153
	v_exp_f32_e32 v151, v151
	v_rcp_f32_e32 v178, v147
	v_add_f32_e32 v147, 1.0, v177
	v_add_f32_e32 v177, 1.0, v179
	v_mul_f32_e32 v179, 0x3d372713, v15
	v_exp_f32_e32 v153, v153
	v_mul_f32_e32 v179, v15, v179
	v_fma_f32 v179, v15, v179, v15
	v_mul_f32_e32 v179, 0xc0135761, v179
	v_rcp_f32_e32 v194, v150
	v_add_f32_e32 v150, 1.0, v151
	v_mul_f32_e32 v151, 0x3d372713, v7
	v_rcp_f32_e32 v195, v150
	v_add_f32_e32 v150, 1.0, v153
	v_mul_f32_e32 v151, v7, v151
	v_mul_f32_e32 v153, 0x3d372713, v3
	v_exp_f32_e32 v179, v179
	v_fma_f32 v151, v7, v151, v7
	v_mul_f32_e32 v153, v3, v153
	v_mul_f32_e32 v151, 0xc0135761, v151
	v_fma_f32 v153, v3, v153, v3
	v_mul_f32_e32 v153, 0xc0135761, v153
	v_exp_f32_e32 v151, v151
	v_add_f32_e32 v179, 1.0, v179
	v_exp_f32_e32 v153, v153
	v_rcp_f32_e32 v177, v177
	v_rcp_f32_e32 v179, v179
	v_rcp_f32_e32 v196, v150
	v_add_f32_e32 v150, 1.0, v151
	v_rcp_f32_e32 v147, v147
	v_rcp_f32_e32 v197, v150
	v_add_f32_e32 v150, 1.0, v153
	v_rcp_f32_e32 v198, v150
	v_mul_f32_e32 v182, v10, v177
	v_mul_f32_e32 v184, v15, v179
	v_mov_b32_e32 v150, v13
	v_mov_b32_e32 v151, v174
	v_mov_b32_e32 v177, v174
	v_mov_b32_e32 v190, v9
	v_mov_b32_e32 v191, v175
	v_mov_b32_e32 v179, v175
	v_pk_mul_f32 v[188:189], v[150:151], v[176:177]
	v_pk_mul_f32 v[178:179], v[190:191], v[178:179]
	v_rcp_f32_e32 v136, v136
	v_pk_fma_f32 v[150:151], v[150:151], v[176:177], v[178:179]
	v_pk_mul_f32 v[176:177], v[188:189], v[188:189]
	v_pk_mul_f32 v[190:191], v[178:179], v[178:179]
	v_mul_f32_e32 v172, v14, v147
	v_mov_b32_e32 v153, v176
	v_mov_b32_e32 v176, v137
	v_mov_b32_e32 v177, v190
	v_mul_f32_e32 v186, v11, v183
	v_pk_add_f32 v[152:153], v[152:153], v[176:177]
	v_mul_f32_e32 v173, v172, v172
	v_mul_f32_e32 v183, v182, v182
	v_pk_add_f32 v[150:151], v[150:151], v[152:153]
	v_pk_add_f32 v[152:153], v[172:173], v[182:183]
	v_mul_f32_e32 v185, v184, v184
	v_mul_f32_e32 v187, v186, v186
	v_pk_add_f32 v[150:151], v[152:153], v[150:151]
	v_pk_add_f32 v[152:153], v[184:185], v[186:187]
	v_mul_f32_e32 v176, v0, v192
	v_pk_add_f32 v[152:153], v[152:153], v[150:151]
	v_cvt_pk_bf16_f32 v150, v174, v188
	v_cvt_pk_bf16_f32 v151, v172, v184
	v_mul_f32_e32 v172, v4, v136
	v_mul_f32_e32 v184, v5, v193
	v_mul_f32_e32 v188, v1, v194
	v_mul_f32_e32 v173, v172, v172
	v_mul_f32_e32 v177, v176, v176
	v_mul_f32_e32 v190, v6, v195
	v_mul_f32_e32 v192, v2, v196
	v_mul_f32_e32 v196, v3, v198
	v_pk_add_f32 v[198:199], v[172:173], v[176:177]
	v_mul_f32_e32 v185, v184, v184
	v_mul_f32_e32 v189, v188, v188
	v_mul_f32_e32 v194, v7, v197
	v_pk_add_f32 v[152:153], v[152:153], v[198:199]
	v_pk_add_f32 v[198:199], v[184:185], v[188:189]
	v_mul_f32_e32 v191, v190, v190
	v_mul_f32_e32 v193, v192, v192
	v_pk_add_f32 v[152:153], v[198:199], v[152:153]
	v_pk_add_f32 v[198:199], v[190:191], v[192:193]
	v_mul_f32_e32 v195, v194, v194
	v_mul_f32_e32 v197, v196, v196
	v_pk_add_f32 v[152:153], v[198:199], v[152:153]
	v_pk_add_f32 v[198:199], v[194:195], v[196:197]
	s_nop 0
	v_pk_add_f32 v[198:199], v[198:199], v[152:153]
	ds_bpermute_b32 v200, v170, v198
	ds_bpermute_b32 v201, v170, v199
	v_cvt_pk_bf16_f32 v152, v175, v178
	v_cvt_pk_bf16_f32 v153, v182, v186
	global_store_dwordx4 v[180:181], v[150:153], off
	v_cvt_pk_bf16_f32 v170, v172, v184
	s_waitcnt lgkmcnt(0)
	s_nop 0
	v_pk_add_f32 v[150:151], v[198:199], v[200:201]
	ds_bpermute_b32 v152, v171, v150
	ds_bpermute_b32 v153, v171, v151
	v_cvt_pk_bf16_f32 v171, v190, v194
	v_cvt_pk_bf16_f32 v172, v176, v188
	v_cvt_pk_bf16_f32 v173, v192, v196
	global_store_dwordx4 v[180:181], v[170:173], off offset:256
	s_and_saveexec_b64 s[72:73], s[4:5]
	s_cbranch_execz .LBB0_177
	v_lshlrev_b64 v[148:149], 8, v[148:149]
	v_lshl_add_u64 v[148:149], s[16:17], 0, v[148:149]
	s_waitcnt lgkmcnt(0)
	v_pk_add_f32 v[150:151], v[150:151], v[152:153]
	v_lshl_add_u64 v[148:149], s[18:19], 3, v[148:149]
	global_store_dwordx2 v[148:149], v[150:151], off

; __device__ __forceinline__ float silu_f(float v) { return v * fast_sigmoid(v); }
; __device__ __forceinline__ float gelu_f(float v) { const float u = 1.5957691216057308f * (v + 0.044715f * v * v * v); return v * fast_sigmoid(u); }
; __device__ __forceinline__ u32x4 pack8(const f32x4 a, const f32x4 b) { u32x4 w; w.x = cvt_pk_bf16(a[0], a[1]); w.y = cvt_pk_bf16(a[2], a[3]); w.z = cvt_pk_bf16(b[0], b[1]); w.w = cvt_pk_bf16(b[2], b[3]); return w; }
;     __device__ __forceinline__ void operator()(const Acc& acc, const Unit& u, int wr, int wc, int fr, int fq) const {
;         if (u.pn < 16) {
;             const int cb = u.pn * 128 + wc * 32 + 8 * fq;
; #pragma unroll
;             for (int ai = 0; ai < 2; ++ai)
; #pragma unroll
;                 for (int m = 0; m < 4; ++m) {
;                     const int row = u.pm * 256 + ai * 128 + wr * 64 + m * 16 + fr;
;                     f32x4 a0 = acc[ai][0][m][0], a1 = acc[ai][0][m][1]; const f32x4 z0 = acc[ai][1][m][0], z1 = acc[ai][1][m][1];
; #pragma unroll
;                     for (int j = 0; j < 4; ++j) { a0[j] = gelu_f(a0[j]) * silu_f(z0[j]); a1[j] = gelu_f(a1[j]) * silu_f(z1[j]); }
;                     *(u32x4*)(UZ + (size_t)row * DM + cb) = pack8(a0, a1);
;                 }
.LBB0_178:
	v_fma_f32 v136, v124, v169, v124
	v_mul_f32_e32 v136, 0xc0135761, v136
	v_exp_f32_e32 v136, v136
	v_mul_f32_e32 v147, 0xbfb8aa3b, v116
	v_exp_f32_e32 v147, v147
	s_waitcnt lgkmcnt(0)
	v_mov_b32_e32 v153, v116
	v_add_f32_e32 v136, 1.0, v136
	v_rcp_f32_e32 v150, v136
	v_add_f32_e32 v136, 1.0, v147
	v_fma_f32 v116, v120, v168, v120
	v_rcp_f32_e32 v151, v136
	v_mul_f32_e32 v116, 0xc0135761, v116
	v_mov_b32_e32 v152, v124
	v_exp_f32_e32 v116, v116
	v_mul_f32_e32 v124, 0xbfb8aa3b, v112
	v_exp_f32_e32 v124, v124
	v_pk_mul_f32 v[150:151], v[152:153], v[150:151]
	v_add_f32_e32 v116, 1.0, v116
	v_mul_f32_e32 v136, v150, v151
	v_mov_b32_e32 v151, v112
	v_fma_f32 v112, v125, v167, v125
	v_mul_f32_e32 v112, 0xc0135761, v112
	v_rcp_f32_e32 v152, v116
	v_add_f32_e32 v116, 1.0, v124
	v_rcp_f32_e32 v153, v116
	v_exp_f32_e32 v112, v112
	v_mul_f32_e32 v116, 0xbfb8aa3b, v117
	v_exp_f32_e32 v116, v116
	v_mov_b32_e32 v150, v120
	v_pk_mul_f32 v[150:151], v[150:151], v[152:153]
	v_add_f32_e32 v112, 1.0, v112
	v_mul_f32_e32 v120, v150, v151
	v_rcp_f32_e32 v150, v112
	v_add_f32_e32 v112, 1.0, v116
	v_rcp_f32_e32 v151, v112
	v_fma_f32 v112, v121, v166, v121
	v_mul_f32_e32 v112, 0xc0135761, v112
	v_exp_f32_e32 v112, v112
	v_mul_f32_e32 v116, 0xbfb8aa3b, v113
	v_exp_f32_e32 v147, v116
	v_mov_b32_e32 v116, v125
	v_add_f32_e32 v112, 1.0, v112
	v_pk_mul_f32 v[116:117], v[116:117], v[150:151]
	v_rcp_f32_e32 v124, v112
	v_add_f32_e32 v112, 1.0, v147
	v_mul_f32_e32 v147, v116, v117
	v_fma_f32 v116, v126, v165, v126
	v_rcp_f32_e32 v125, v112
	v_mul_f32_e32 v116, 0xc0135761, v116
	v_mul_f32_e32 v117, 0xbfb8aa3b, v118
	v_exp_f32_e32 v117, v117
	v_exp_f32_e32 v116, v116
	v_mov_b32_e32 v112, v121
	v_pk_mul_f32 v[112:113], v[112:113], v[124:125]
	v_mul_f32_e32 v124, 0xbfb8aa3b, v114
	v_mul_f32_e32 v121, v112, v113
	v_add_f32_e32 v113, 1.0, v117
	v_mov_b32_e32 v117, v118
	v_fma_f32 v118, v122, v163, v122
	v_add_f32_e32 v112, 1.0, v116
	v_mul_f32_e32 v118, 0xc0135761, v118
	v_rcp_f32_e32 v112, v112
	v_rcp_f32_e32 v113, v113
	v_exp_f32_e32 v118, v118
	v_exp_f32_e32 v124, v124
	v_mov_b32_e32 v116, v126
	v_pk_mul_f32 v[112:113], v[116:117], v[112:113]
	v_add_f32_e32 v116, 1.0, v118
	v_add_f32_e32 v117, 1.0, v124
	v_mul_f32_e32 v124, v112, v113
	v_mov_b32_e32 v113, v114
	v_fma_f32 v114, v127, v162, v127
	v_rcp_f32_e32 v116, v116
	v_rcp_f32_e32 v117, v117
	v_mul_f32_e32 v114, 0xc0135761, v114
	v_exp_f32_e32 v114, v114
	v_mov_b32_e32 v112, v122
	v_pk_mul_f32 v[112:113], v[112:113], v[116:117]
	v_mul_f32_e32 v116, 0xbfb8aa3b, v119
	v_exp_f32_e32 v116, v116
	v_mul_f32_e32 v122, v112, v113
	v_add_f32_e32 v112, 1.0, v114
	v_fma_f32 v114, v123, v161, v123
	v_mul_f32_e32 v114, 0xc0135761, v114
	v_add_f32_e32 v113, 1.0, v116
	v_exp_f32_e32 v114, v114
	v_mul_f32_e32 v116, 0xbfb8aa3b, v115
	v_exp_f32_e32 v117, v116
	v_rcp_f32_e32 v112, v112
	v_add_f32_e32 v114, 1.0, v114
	v_rcp_f32_e32 v113, v113
	v_rcp_f32_e32 v116, v114
	v_add_f32_e32 v114, 1.0, v117
	v_rcp_f32_e32 v117, v114
	v_mov_b32_e32 v118, v127
	v_pk_mul_f32 v[112:113], v[118:119], v[112:113]
	v_mov_b32_e32 v114, v123
	v_mul_f32_e32 v118, v112, v113
	v_pk_mul_f32 v[112:113], v[114:115], v[116:117]
	v_cvt_pk_bf16_f32 v114, v136, v147
	v_cvt_pk_bf16_f32 v115, v124, v118
	v_cvt_pk_bf16_f32 v116, v120, v121
	v_mul_f32_e32 v120, 0x3d372713, v108
	v_mul_f32_e32 v120, v108, v120
	v_fma_f32 v120, v108, v120, v108
	v_mul_f32_e32 v120, 0xc0135761, v120
	v_mul_f32_e32 v121, 0xbfb8aa3b, v100
	v_lshl_or_b32 v148, s70, 7, v156
	v_mul_f32_e32 v112, v112, v113
	v_ashrrev_i32_e32 v147, 31, v146
	v_exp_f32_e32 v120, v120
	v_exp_f32_e32 v121, v121
	v_ashrrev_i32_e32 v149, 31, v148
	v_cvt_pk_bf16_f32 v117, v122, v112
	v_lshlrev_b64 v[112:113], 12, v[146:147]
	v_lshl_add_u64 v[118:119], s[8:9], 0, v[112:113]
	v_lshlrev_b64 v[112:113], 1, v[148:149]
	v_lshl_add_u64 v[118:119], v[118:119], 0, v[112:113]
	global_store_dwordx4 v[118:119], v[114:117], off
	s_nop 1
	v_add_f32_e32 v114, 1.0, v120
	v_add_f32_e32 v115, 1.0, v121
	v_mov_b32_e32 v117, v100
	v_mul_f32_e32 v100, 0x3d372713, v104
	v_rcp_f32_e32 v114, v114
	v_rcp_f32_e32 v115, v115
	v_mul_f32_e32 v100, v104, v100
	v_fma_f32 v100, v104, v100, v104
	v_mul_f32_e32 v100, 0xc0135761, v100
	v_mov_b32_e32 v116, v108
	v_exp_f32_e32 v100, v100
	v_mul_f32_e32 v108, 0xbfb8aa3b, v96
	v_pk_mul_f32 v[114:115], v[116:117], v[114:115]
	v_exp_f32_e32 v108, v108
	v_mul_f32_e32 v118, v114, v115
	v_mov_b32_e32 v115, v96
	v_mul_f32_e32 v96, 0x3d372713, v109
	v_mul_f32_e32 v96, v109, v96
	v_fma_f32 v96, v109, v96, v109
	v_add_f32_e32 v100, 1.0, v100
	v_mul_f32_e32 v96, 0xc0135761, v96
	v_rcp_f32_e32 v116, v100
	v_add_f32_e32 v100, 1.0, v108
	v_rcp_f32_e32 v117, v100
	v_exp_f32_e32 v96, v96
	v_mul_f32_e32 v100, 0xbfb8aa3b, v101
	v_exp_f32_e32 v100, v100
	v_mov_b32_e32 v114, v104
	v_pk_mul_f32 v[114:115], v[114:115], v[116:117]
	v_add_f32_e32 v96, 1.0, v96
	v_mul_f32_e32 v104, v114, v115
	v_rcp_f32_e32 v114, v96
	v_add_f32_e32 v96, 1.0, v100
	v_rcp_f32_e32 v115, v96
	v_mul_f32_e32 v96, 0x3d372713, v105
	v_mul_f32_e32 v96, v105, v96
	v_fma_f32 v96, v105, v96, v105
	v_mul_f32_e32 v96, 0xc0135761, v96
	v_mul_f32_e32 v100, 0xbfb8aa3b, v97
	v_exp_f32_e32 v96, v96
	v_exp_f32_e32 v116, v100
	v_mov_b32_e32 v100, v109
	v_pk_mul_f32 v[100:101], v[100:101], v[114:115]
	v_add_f32_e32 v96, 1.0, v96
	v_mul_f32_e32 v114, v100, v101
	v_mul_f32_e32 v100, 0x3d372713, v110
	v_mul_f32_e32 v100, v110, v100
	v_fma_f32 v100, v110, v100, v110
	v_rcp_f32_e32 v108, v96
	v_add_f32_e32 v96, 1.0, v116
	v_mul_f32_e32 v100, 0xc0135761, v100
	v_rcp_f32_e32 v109, v96
	v_mul_f32_e32 v101, 0xbfb8aa3b, v102
	v_exp_f32_e32 v100, v100
	v_exp_f32_e32 v101, v101
; __device__ __forceinline__ float silu_f(float v) { return v * fast_sigmoid(v); }
; __device__ __forceinline__ float gelu_f(float v) { const float u = 1.5957691216057308f * (v + 0.044715f * v * v * v); return v * fast_sigmoid(u); }
; __device__ __forceinline__ u32x4 pack8(const f32x4 a, const f32x4 b) { u32x4 w; w.x = cvt_pk_bf16(a[0], a[1]); w.y = cvt_pk_bf16(a[2], a[3]); w.z = cvt_pk_bf16(b[0], b[1]); w.w = cvt_pk_bf16(b[2], b[3]); return w; }
;     __device__ __forceinline__ void operator()(const Acc& acc, const Unit& u, int wr, int wc, int fr, int fq) const {
;         if (u.pn < 16) {
;             const int cb = u.pn * 128 + wc * 32 + 8 * fq;
; #pragma unroll
;             for (int ai = 0; ai < 2; ++ai)
; #pragma unroll
;                 for (int m = 0; m < 4; ++m) {
;                     const int row = u.pm * 256 + ai * 128 + wr * 64 + m * 16 + fr;
;                     f32x4 a0 = acc[ai][0][m][0], a1 = acc[ai][0][m][1]; const f32x4 z0 = acc[ai][1][m][0], z1 = acc[ai][1][m][1];
; #pragma unroll
;                     for (int j = 0; j < 4; ++j) { a0[j] = gelu_f(a0[j]) * silu_f(z0[j]); a1[j] = gelu_f(a1[j]) * silu_f(z1[j]); }
;                     *(u32x4*)(UZ + (size_t)row * DM + cb) = pack8(a0, a1);
;                 }
	v_mov_b32_e32 v96, v105
	v_pk_mul_f32 v[96:97], v[96:97], v[108:109]
	v_mul_f32_e32 v108, 0xbfb8aa3b, v98
	v_mul_f32_e32 v105, v96, v97
	v_add_f32_e32 v96, 1.0, v100
	v_add_f32_e32 v97, 1.0, v101
	v_mov_b32_e32 v101, v102
	v_mul_f32_e32 v102, 0x3d372713, v106
	v_rcp_f32_e32 v96, v96
	v_rcp_f32_e32 v97, v97
	v_mul_f32_e32 v102, v106, v102
	v_fma_f32 v102, v106, v102, v106
	v_exp_f32_e32 v108, v108
	v_mul_f32_e32 v102, 0xc0135761, v102
	v_mov_b32_e32 v100, v110
	v_exp_f32_e32 v102, v102
	v_pk_mul_f32 v[96:97], v[100:101], v[96:97]
	v_add_f32_e32 v101, 1.0, v108
	v_mul_f32_e32 v108, v96, v97
	v_mov_b32_e32 v97, v98
	v_mul_f32_e32 v98, 0x3d372713, v111
	v_mul_f32_e32 v98, v111, v98
	v_fma_f32 v98, v111, v98, v111
	v_add_f32_e32 v100, 1.0, v102
	v_mul_f32_e32 v98, 0xc0135761, v98
	v_rcp_f32_e32 v100, v100
	v_rcp_f32_e32 v101, v101
	v_exp_f32_e32 v98, v98
	v_mov_b32_e32 v96, v106
	v_pk_mul_f32 v[96:97], v[96:97], v[100:101]
	v_mul_f32_e32 v100, 0xbfb8aa3b, v103
	v_mul_f32_e32 v106, v96, v97
	v_add_f32_e32 v96, 1.0, v98
	v_mul_f32_e32 v98, 0x3d372713, v107
	v_exp_f32_e32 v100, v100
	v_mul_f32_e32 v98, v107, v98
	v_fma_f32 v98, v107, v98, v107
	v_mul_f32_e32 v98, 0xc0135761, v98
	v_add_f32_e32 v97, 1.0, v100
	v_exp_f32_e32 v98, v98
	v_mul_f32_e32 v100, 0xbfb8aa3b, v99
	v_exp_f32_e32 v101, v100
	v_rcp_f32_e32 v96, v96
	v_add_f32_e32 v98, 1.0, v98
	v_rcp_f32_e32 v97, v97
	v_rcp_f32_e32 v100, v98
	v_add_f32_e32 v98, 1.0, v101
	v_rcp_f32_e32 v101, v98
	v_mov_b32_e32 v102, v111
	v_pk_mul_f32 v[96:97], v[102:103], v[96:97]
	v_mov_b32_e32 v98, v107
	v_mul_f32_e32 v102, v96, v97
	v_pk_mul_f32 v[96:97], v[98:99], v[100:101]
	v_or_b32_e32 v100, 16, v146
	v_mul_f32_e32 v99, v96, v97
	v_cvt_pk_bf16_f32 v96, v118, v114
	v_cvt_pk_bf16_f32 v97, v108, v102
	v_mul_f32_e32 v102, 0x3d372713, v92
	v_mul_f32_e32 v102, v92, v102
	v_fma_f32 v102, v92, v102, v92
	v_mul_f32_e32 v102, 0xc0135761, v102
	v_mul_f32_e32 v103, 0xbfb8aa3b, v84
	v_ashrrev_i32_e32 v101, 31, v100
	v_exp_f32_e32 v102, v102
	v_exp_f32_e32 v103, v103
	v_lshlrev_b64 v[100:101], 12, v[100:101]
	v_lshl_add_u64 v[100:101], s[8:9], 0, v[100:101]
	v_cvt_pk_bf16_f32 v98, v104, v105
	v_cvt_pk_bf16_f32 v99, v106, v99
	v_lshl_add_u64 v[100:101], v[100:101], 0, v[112:113]
	global_store_dwordx4 v[100:101], v[96:99], off
	s_nop 1
	v_add_f32_e32 v96, 1.0, v102
	v_add_f32_e32 v97, 1.0, v103
	v_mov_b32_e32 v99, v84
	v_mul_f32_e32 v84, 0x3d372713, v88
	v_rcp_f32_e32 v96, v96
	v_rcp_f32_e32 v97, v97
	v_mul_f32_e32 v84, v88, v84
	v_fma_f32 v84, v88, v84, v88
	v_mul_f32_e32 v84, 0xc0135761, v84
	v_mov_b32_e32 v98, v92
	v_exp_f32_e32 v84, v84
	v_mul_f32_e32 v92, 0xbfb8aa3b, v80
	v_pk_mul_f32 v[96:97], v[98:99], v[96:97]
	v_exp_f32_e32 v92, v92
	v_mul_f32_e32 v100, v96, v97
	v_mov_b32_e32 v97, v80
	v_mul_f32_e32 v80, 0x3d372713, v93
	v_mul_f32_e32 v80, v93, v80
	v_fma_f32 v80, v93, v80, v93
	v_add_f32_e32 v84, 1.0, v84
	v_mul_f32_e32 v80, 0xc0135761, v80
	v_rcp_f32_e32 v98, v84
	v_add_f32_e32 v84, 1.0, v92
	v_rcp_f32_e32 v99, v84
	v_exp_f32_e32 v80, v80
	v_mul_f32_e32 v84, 0xbfb8aa3b, v85
	v_exp_f32_e32 v84, v84
	v_mov_b32_e32 v96, v88
	v_pk_mul_f32 v[96:97], v[96:97], v[98:99]
	v_add_f32_e32 v80, 1.0, v80
	v_mul_f32_e32 v88, v96, v97
	v_rcp_f32_e32 v96, v80
	v_add_f32_e32 v80, 1.0, v84
	v_rcp_f32_e32 v97, v80
	v_mul_f32_e32 v80, 0x3d372713, v89
	v_mul_f32_e32 v80, v89, v80
	v_fma_f32 v80, v89, v80, v89
	v_mul_f32_e32 v80, 0xc0135761, v80
	v_mul_f32_e32 v84, 0xbfb8aa3b, v81
	v_exp_f32_e32 v80, v80
	v_exp_f32_e32 v98, v84
	v_mov_b32_e32 v84, v93
	v_pk_mul_f32 v[84:85], v[84:85], v[96:97]
	v_add_f32_e32 v80, 1.0, v80
	v_mul_f32_e32 v96, v84, v85
	v_mul_f32_e32 v84, 0x3d372713, v94
	v_mul_f32_e32 v84, v94, v84
	v_fma_f32 v84, v94, v84, v94
	v_rcp_f32_e32 v92, v80
	v_add_f32_e32 v80, 1.0, v98
	v_mul_f32_e32 v84, 0xc0135761, v84
	v_rcp_f32_e32 v93, v80
	v_mul_f32_e32 v85, 0xbfb8aa3b, v86
	v_exp_f32_e32 v84, v84
	v_exp_f32_e32 v85, v85
	v_mov_b32_e32 v80, v89
	v_pk_mul_f32 v[80:81], v[80:81], v[92:93]
	v_mul_f32_e32 v92, 0xbfb8aa3b, v82
	v_mul_f32_e32 v89, v80, v81
	v_add_f32_e32 v80, 1.0, v84
	v_add_f32_e32 v81, 1.0, v85
	v_mov_b32_e32 v85, v86
	v_mul_f32_e32 v86, 0x3d372713, v90
	v_rcp_f32_e32 v80, v80
	v_rcp_f32_e32 v81, v81
	v_mul_f32_e32 v86, v90, v86
	v_fma_f32 v86, v90, v86, v90
	v_exp_f32_e32 v92, v92
	v_mul_f32_e32 v86, 0xc0135761, v86
	v_mov_b32_e32 v84, v94
	v_exp_f32_e32 v86, v86
	v_pk_mul_f32 v[80:81], v[84:85], v[80:81]
	v_add_f32_e32 v85, 1.0, v92
	v_mul_f32_e32 v92, v80, v81
	v_mov_b32_e32 v81, v82
	v_mul_f32_e32 v82, 0x3d372713, v95
	v_mul_f32_e32 v82, v95, v82
	v_fma_f32 v82, v95, v82, v95
	v_add_f32_e32 v84, 1.0, v86
	v_mul_f32_e32 v82, 0xc0135761, v82
	v_rcp_f32_e32 v84, v84
	v_rcp_f32_e32 v85, v85
	v_exp_f32_e32 v82, v82
	v_mov_b32_e32 v80, v90
	v_pk_mul_f32 v[80:81], v[80:81], v[84:85]
	v_mul_f32_e32 v84, 0xbfb8aa3b, v87
	v_mul_f32_e32 v90, v80, v81
	v_add_f32_e32 v80, 1.0, v82
	v_mul_f32_e32 v82, 0x3d372713, v91
	v_exp_f32_e32 v84, v84
	v_mul_f32_e32 v82, v91, v82
	v_fma_f32 v82, v91, v82, v91
	v_mul_f32_e32 v82, 0xc0135761, v82
	v_add_f32_e32 v81, 1.0, v84
	v_exp_f32_e32 v82, v82
	v_mul_f32_e32 v84, 0xbfb8aa3b, v83
	v_exp_f32_e32 v85, v84
	v_rcp_f32_e32 v80, v80
	v_add_f32_e32 v82, 1.0, v82
	v_rcp_f32_e32 v81, v81
	v_rcp_f32_e32 v84, v82
	v_add_f32_e32 v82, 1.0, v85
	v_rcp_f32_e32 v85, v82
	v_mov_b32_e32 v86, v95
	v_pk_mul_f32 v[80:81], v[86:87], v[80:81]
	v_mov_b32_e32 v82, v91
	v_mul_f32_e32 v86, v80, v81
	v_pk_mul_f32 v[80:81], v[82:83], v[84:85]
	v_or_b32_e32 v84, 32, v146
	v_mul_f32_e32 v83, v80, v81
	v_cvt_pk_bf16_f32 v80, v100, v96
	v_cvt_pk_bf16_f32 v81, v92, v86
	v_mul_f32_e32 v86, 0x3d372713, v76
; __device__ __forceinline__ float silu_f(float v) { return v * fast_sigmoid(v); }
; __device__ __forceinline__ float gelu_f(float v) { const float u = 1.5957691216057308f * (v + 0.044715f * v * v * v); return v * fast_sigmoid(u); }
; __device__ __forceinline__ u32x4 pack8(const f32x4 a, const f32x4 b) { u32x4 w; w.x = cvt_pk_bf16(a[0], a[1]); w.y = cvt_pk_bf16(a[2], a[3]); w.z = cvt_pk_bf16(b[0], b[1]); w.w = cvt_pk_bf16(b[2], b[3]); return w; }
;     __device__ __forceinline__ void operator()(const Acc& acc, const Unit& u, int wr, int wc, int fr, int fq) const {
;         if (u.pn < 16) {
;             const int cb = u.pn * 128 + wc * 32 + 8 * fq;
; #pragma unroll
;             for (int ai = 0; ai < 2; ++ai)
; #pragma unroll
;                 for (int m = 0; m < 4; ++m) {
;                     const int row = u.pm * 256 + ai * 128 + wr * 64 + m * 16 + fr;
;                     f32x4 a0 = acc[ai][0][m][0], a1 = acc[ai][0][m][1]; const f32x4 z0 = acc[ai][1][m][0], z1 = acc[ai][1][m][1];
; #pragma unroll
;                     for (int j = 0; j < 4; ++j) { a0[j] = gelu_f(a0[j]) * silu_f(z0[j]); a1[j] = gelu_f(a1[j]) * silu_f(z1[j]); }
;                     *(u32x4*)(UZ + (size_t)row * DM + cb) = pack8(a0, a1);
;                 }
	v_mul_f32_e32 v86, v76, v86
	v_fma_f32 v86, v76, v86, v76
	v_mul_f32_e32 v86, 0xc0135761, v86
	v_mul_f32_e32 v87, 0xbfb8aa3b, v68
	v_ashrrev_i32_e32 v85, 31, v84
	v_exp_f32_e32 v86, v86
	v_exp_f32_e32 v87, v87
	v_lshlrev_b64 v[84:85], 12, v[84:85]
	v_lshl_add_u64 v[84:85], s[8:9], 0, v[84:85]
	v_cvt_pk_bf16_f32 v82, v88, v89
	v_cvt_pk_bf16_f32 v83, v90, v83
	v_lshl_add_u64 v[84:85], v[84:85], 0, v[112:113]
	global_store_dwordx4 v[84:85], v[80:83], off
	s_nop 1
	v_add_f32_e32 v80, 1.0, v86
	v_add_f32_e32 v81, 1.0, v87
	v_mov_b32_e32 v83, v68
	v_mul_f32_e32 v68, 0x3d372713, v72
	v_rcp_f32_e32 v80, v80
	v_rcp_f32_e32 v81, v81
	v_mul_f32_e32 v68, v72, v68
	v_fma_f32 v68, v72, v68, v72
	v_mul_f32_e32 v68, 0xc0135761, v68
	v_mov_b32_e32 v82, v76
	v_exp_f32_e32 v68, v68
	v_mul_f32_e32 v76, 0xbfb8aa3b, v64
	v_pk_mul_f32 v[80:81], v[82:83], v[80:81]
	v_exp_f32_e32 v76, v76
	v_mul_f32_e32 v84, v80, v81
	v_mov_b32_e32 v81, v64
	v_mul_f32_e32 v64, 0x3d372713, v77
	v_mul_f32_e32 v64, v77, v64
	v_fma_f32 v64, v77, v64, v77
	v_add_f32_e32 v68, 1.0, v68
	v_mul_f32_e32 v64, 0xc0135761, v64
	v_rcp_f32_e32 v82, v68
	v_add_f32_e32 v68, 1.0, v76
	v_rcp_f32_e32 v83, v68
	v_exp_f32_e32 v64, v64
	v_mul_f32_e32 v68, 0xbfb8aa3b, v69
	v_exp_f32_e32 v68, v68
	v_mov_b32_e32 v80, v72
	v_pk_mul_f32 v[80:81], v[80:81], v[82:83]
	v_add_f32_e32 v64, 1.0, v64
	v_mul_f32_e32 v72, v80, v81
	v_rcp_f32_e32 v80, v64
	v_add_f32_e32 v64, 1.0, v68
	v_rcp_f32_e32 v81, v64
	v_mul_f32_e32 v64, 0x3d372713, v73
	v_mul_f32_e32 v64, v73, v64
	v_fma_f32 v64, v73, v64, v73
	v_mul_f32_e32 v64, 0xc0135761, v64
	v_mul_f32_e32 v68, 0xbfb8aa3b, v65
	v_exp_f32_e32 v64, v64
	v_exp_f32_e32 v82, v68
	v_mov_b32_e32 v68, v77
	v_pk_mul_f32 v[68:69], v[68:69], v[80:81]
	v_add_f32_e32 v64, 1.0, v64
	v_mul_f32_e32 v80, v68, v69
	v_mul_f32_e32 v68, 0x3d372713, v78
	v_mul_f32_e32 v68, v78, v68
	v_fma_f32 v68, v78, v68, v78
	v_rcp_f32_e32 v76, v64
	v_add_f32_e32 v64, 1.0, v82
	v_mul_f32_e32 v68, 0xc0135761, v68
	v_rcp_f32_e32 v77, v64
	v_mul_f32_e32 v69, 0xbfb8aa3b, v70
	v_exp_f32_e32 v68, v68
	v_exp_f32_e32 v69, v69
	v_mov_b32_e32 v64, v73
	v_pk_mul_f32 v[64:65], v[64:65], v[76:77]
	v_mul_f32_e32 v76, 0xbfb8aa3b, v66
	v_mul_f32_e32 v73, v64, v65
	v_add_f32_e32 v64, 1.0, v68
	v_add_f32_e32 v65, 1.0, v69
	v_mov_b32_e32 v69, v70
	v_mul_f32_e32 v70, 0x3d372713, v74
	v_rcp_f32_e32 v64, v64
	v_rcp_f32_e32 v65, v65
	v_mul_f32_e32 v70, v74, v70
	v_fma_f32 v70, v74, v70, v74
	v_exp_f32_e32 v76, v76
	v_mul_f32_e32 v70, 0xc0135761, v70
	v_mov_b32_e32 v68, v78
	v_exp_f32_e32 v70, v70
	v_pk_mul_f32 v[64:65], v[68:69], v[64:65]
	v_add_f32_e32 v69, 1.0, v76
	v_mul_f32_e32 v76, v64, v65
	v_mov_b32_e32 v65, v66
	v_mul_f32_e32 v66, 0x3d372713, v79
	v_mul_f32_e32 v66, v79, v66
	v_fma_f32 v66, v79, v66, v79
	v_add_f32_e32 v68, 1.0, v70
	v_mul_f32_e32 v66, 0xc0135761, v66
	v_rcp_f32_e32 v68, v68
	v_rcp_f32_e32 v69, v69
	v_exp_f32_e32 v66, v66
	v_mov_b32_e32 v64, v74
	v_pk_mul_f32 v[64:65], v[64:65], v[68:69]
	v_mul_f32_e32 v68, 0xbfb8aa3b, v71
	v_mul_f32_e32 v74, v64, v65
	v_add_f32_e32 v64, 1.0, v66
	v_mul_f32_e32 v66, 0x3d372713, v75
	v_exp_f32_e32 v68, v68
	v_mul_f32_e32 v66, v75, v66
	v_fma_f32 v66, v75, v66, v75
	v_mul_f32_e32 v66, 0xc0135761, v66
	v_add_f32_e32 v65, 1.0, v68
	v_exp_f32_e32 v66, v66
	v_mul_f32_e32 v68, 0xbfb8aa3b, v67
	v_exp_f32_e32 v69, v68
	v_rcp_f32_e32 v64, v64
	v_add_f32_e32 v66, 1.0, v66
	v_rcp_f32_e32 v65, v65
	v_rcp_f32_e32 v68, v66
	v_add_f32_e32 v66, 1.0, v69
	v_rcp_f32_e32 v69, v66
	v_mov_b32_e32 v70, v79
	v_pk_mul_f32 v[64:65], v[70:71], v[64:65]
	v_mov_b32_e32 v66, v75
	v_mul_f32_e32 v70, v64, v65
	v_pk_mul_f32 v[64:65], v[66:67], v[68:69]
	v_or_b32_e32 v68, 48, v146
	v_ashrrev_i32_e32 v69, 31, v68
	v_lshlrev_b64 v[68:69], 12, v[68:69]
	v_lshl_add_u64 v[68:69], s[8:9], 0, v[68:69]
	v_mul_f32_e32 v67, v64, v65
	v_cvt_pk_bf16_f32 v64, v84, v80
	v_lshl_add_u64 v[68:69], v[68:69], 0, v[112:113]
	v_cvt_pk_bf16_f32 v65, v76, v70
	v_cvt_pk_bf16_f32 v66, v72, v73
	v_cvt_pk_bf16_f32 v67, v74, v67
	global_store_dwordx4 v[68:69], v[64:67], off
	v_mov_b32_e32 v69, v52
	v_mov_b32_e32 v68, v60
	v_mul_f32_e32 v64, 0x3d372713, v60
	v_mul_f32_e32 v64, v60, v64
	v_fma_f32 v64, v60, v64, v60
	v_mul_f32_e32 v64, 0xc0135761, v64
	v_exp_f32_e32 v65, v64
	v_mul_f32_e32 v64, 0xbfb8aa3b, v52
	v_exp_f32_e32 v67, v64
	v_mul_f32_e32 v52, 0x3d372713, v56
	v_add_f32_e32 v65, 1.0, v65
	v_rcp_f32_e32 v66, v65
	v_add_f32_e32 v65, 1.0, v67
	v_rcp_f32_e32 v67, v65
	v_mul_f32_e32 v52, v56, v52
	v_fma_f32 v52, v56, v52, v56
	v_mul_f32_e32 v52, 0xc0135761, v52
	v_exp_f32_e32 v52, v52
	v_mul_f32_e32 v60, 0xbfb8aa3b, v48
	v_pk_mul_f32 v[66:67], v[68:69], v[66:67]
	v_exp_f32_e32 v60, v60
	v_mul_f32_e32 v65, v66, v67
	v_mov_b32_e32 v67, v48
	v_mul_f32_e32 v48, 0x3d372713, v61
	v_mul_f32_e32 v48, v61, v48
	v_fma_f32 v48, v61, v48, v61
	v_add_f32_e32 v52, 1.0, v52
	v_mul_f32_e32 v48, 0xc0135761, v48
	v_rcp_f32_e32 v68, v52
	v_add_f32_e32 v52, 1.0, v60
	v_rcp_f32_e32 v69, v52
	v_exp_f32_e32 v48, v48
	v_mul_f32_e32 v52, 0xbfb8aa3b, v53
	v_exp_f32_e32 v52, v52
	v_mov_b32_e32 v66, v56
	v_pk_mul_f32 v[66:67], v[66:67], v[68:69]
	v_add_f32_e32 v48, 1.0, v48
	v_mul_f32_e32 v56, v66, v67
	v_rcp_f32_e32 v66, v48
	v_add_f32_e32 v48, 1.0, v52
	v_rcp_f32_e32 v67, v48
	v_mul_f32_e32 v48, 0x3d372713, v57
	v_mul_f32_e32 v48, v57, v48
	v_fma_f32 v48, v57, v48, v57
	v_mul_f32_e32 v48, 0xc0135761, v48
	v_mul_f32_e32 v52, 0xbfb8aa3b, v49
	v_exp_f32_e32 v48, v48
	v_exp_f32_e32 v68, v52
	v_mov_b32_e32 v52, v61
	v_pk_mul_f32 v[52:53], v[52:53], v[66:67]
	v_add_f32_e32 v48, 1.0, v48
	v_mul_f32_e32 v66, v52, v53
	v_mul_f32_e32 v52, 0x3d372713, v62
; __device__ __forceinline__ float silu_f(float v) { return v * fast_sigmoid(v); }
; __device__ __forceinline__ float gelu_f(float v) { const float u = 1.5957691216057308f * (v + 0.044715f * v * v * v); return v * fast_sigmoid(u); }
; __device__ __forceinline__ u32x4 pack8(const f32x4 a, const f32x4 b) { u32x4 w; w.x = cvt_pk_bf16(a[0], a[1]); w.y = cvt_pk_bf16(a[2], a[3]); w.z = cvt_pk_bf16(b[0], b[1]); w.w = cvt_pk_bf16(b[2], b[3]); return w; }
;     __device__ __forceinline__ void operator()(const Acc& acc, const Unit& u, int wr, int wc, int fr, int fq) const {
;         if (u.pn < 16) {
;             const int cb = u.pn * 128 + wc * 32 + 8 * fq;
; #pragma unroll
;             for (int ai = 0; ai < 2; ++ai)
; #pragma unroll
;                 for (int m = 0; m < 4; ++m) {
;                     const int row = u.pm * 256 + ai * 128 + wr * 64 + m * 16 + fr;
;                     f32x4 a0 = acc[ai][0][m][0], a1 = acc[ai][0][m][1]; const f32x4 z0 = acc[ai][1][m][0], z1 = acc[ai][1][m][1];
; #pragma unroll
;                     for (int j = 0; j < 4; ++j) { a0[j] = gelu_f(a0[j]) * silu_f(z0[j]); a1[j] = gelu_f(a1[j]) * silu_f(z1[j]); }
;                     *(u32x4*)(UZ + (size_t)row * DM + cb) = pack8(a0, a1);
;                 }
	v_mul_f32_e32 v52, v62, v52
	v_fma_f32 v52, v62, v52, v62
	v_rcp_f32_e32 v60, v48
	v_add_f32_e32 v48, 1.0, v68
	v_mul_f32_e32 v52, 0xc0135761, v52
	v_rcp_f32_e32 v61, v48
	v_mul_f32_e32 v53, 0xbfb8aa3b, v54
	v_exp_f32_e32 v52, v52
	v_exp_f32_e32 v53, v53
	v_mov_b32_e32 v48, v57
	v_pk_mul_f32 v[48:49], v[48:49], v[60:61]
	v_mul_f32_e32 v60, 0xbfb8aa3b, v50
	v_mul_f32_e32 v57, v48, v49
	v_add_f32_e32 v48, 1.0, v52
	v_add_f32_e32 v49, 1.0, v53
	v_mov_b32_e32 v53, v54
	v_mul_f32_e32 v54, 0x3d372713, v58
	v_rcp_f32_e32 v48, v48
	v_rcp_f32_e32 v49, v49
	v_mul_f32_e32 v54, v58, v54
	v_fma_f32 v54, v58, v54, v58
	v_exp_f32_e32 v60, v60
	v_mul_f32_e32 v54, 0xc0135761, v54
	v_mov_b32_e32 v52, v62
	v_exp_f32_e32 v54, v54
	v_pk_mul_f32 v[48:49], v[52:53], v[48:49]
	v_add_f32_e32 v53, 1.0, v60
	v_mul_f32_e32 v60, v48, v49
	v_mov_b32_e32 v49, v50
	v_mul_f32_e32 v50, 0x3d372713, v63
	v_mul_f32_e32 v50, v63, v50
	v_fma_f32 v50, v63, v50, v63
	v_add_f32_e32 v52, 1.0, v54
	v_mul_f32_e32 v50, 0xc0135761, v50
	v_rcp_f32_e32 v52, v52
	v_rcp_f32_e32 v53, v53
	v_exp_f32_e32 v50, v50
	v_mov_b32_e32 v48, v58
	v_pk_mul_f32 v[48:49], v[48:49], v[52:53]
	v_mul_f32_e32 v52, 0xbfb8aa3b, v55
	v_mul_f32_e32 v58, v48, v49
	v_add_f32_e32 v48, 1.0, v50
	v_mul_f32_e32 v50, 0x3d372713, v59
	v_exp_f32_e32 v52, v52
	v_mul_f32_e32 v50, v59, v50
	v_fma_f32 v50, v59, v50, v59
	v_mul_f32_e32 v50, 0xc0135761, v50
	v_add_f32_e32 v49, 1.0, v52
	v_exp_f32_e32 v50, v50
	v_mul_f32_e32 v52, 0xbfb8aa3b, v51
	v_exp_f32_e32 v53, v52
	v_rcp_f32_e32 v48, v48
	v_add_f32_e32 v50, 1.0, v50
	v_rcp_f32_e32 v49, v49
	v_rcp_f32_e32 v52, v50
	v_add_f32_e32 v50, 1.0, v53
	v_rcp_f32_e32 v53, v50
	v_mov_b32_e32 v54, v63
	v_pk_mul_f32 v[48:49], v[54:55], v[48:49]
	v_mov_b32_e32 v50, v59
	v_mul_f32_e32 v54, v48, v49
	v_pk_mul_f32 v[48:49], v[50:51], v[52:53]
	v_add_u32_e32 v64, 0x80, v146
	v_mul_f32_e32 v51, v48, v49
	v_cvt_pk_bf16_f32 v48, v65, v66
	v_cvt_pk_bf16_f32 v49, v60, v54
	v_mul_f32_e32 v54, 0x3d372713, v44
	v_mul_f32_e32 v54, v44, v54
	v_fma_f32 v54, v44, v54, v44
	v_mul_f32_e32 v54, 0xc0135761, v54
	v_mul_f32_e32 v55, 0xbfb8aa3b, v36
	v_ashrrev_i32_e32 v65, 31, v64
	v_exp_f32_e32 v54, v54
	v_exp_f32_e32 v55, v55
	v_lshlrev_b64 v[52:53], 12, v[64:65]
	v_lshl_add_u64 v[52:53], s[8:9], 0, v[52:53]
	v_cvt_pk_bf16_f32 v50, v56, v57
	v_cvt_pk_bf16_f32 v51, v58, v51
	v_lshl_add_u64 v[52:53], v[52:53], 0, v[112:113]
	global_store_dwordx4 v[52:53], v[48:51], off
	s_nop 1
	v_add_f32_e32 v48, 1.0, v54
	v_add_f32_e32 v49, 1.0, v55
	v_mov_b32_e32 v51, v36
	v_mul_f32_e32 v36, 0x3d372713, v40
	v_rcp_f32_e32 v48, v48
	v_rcp_f32_e32 v49, v49
	v_mul_f32_e32 v36, v40, v36
	v_fma_f32 v36, v40, v36, v40
	v_mul_f32_e32 v36, 0xc0135761, v36
	v_mov_b32_e32 v50, v44
	v_exp_f32_e32 v36, v36
	v_mul_f32_e32 v44, 0xbfb8aa3b, v32
	v_pk_mul_f32 v[48:49], v[50:51], v[48:49]
	v_exp_f32_e32 v44, v44
	v_mul_f32_e32 v52, v48, v49
	v_mov_b32_e32 v49, v32
	v_mul_f32_e32 v32, 0x3d372713, v45
	v_mul_f32_e32 v32, v45, v32
	v_fma_f32 v32, v45, v32, v45
	v_add_f32_e32 v36, 1.0, v36
	v_mul_f32_e32 v32, 0xc0135761, v32
	v_rcp_f32_e32 v50, v36
	v_add_f32_e32 v36, 1.0, v44
	v_rcp_f32_e32 v51, v36
	v_exp_f32_e32 v32, v32
	v_mul_f32_e32 v36, 0xbfb8aa3b, v37
	v_exp_f32_e32 v36, v36
	v_mov_b32_e32 v48, v40
	v_pk_mul_f32 v[48:49], v[48:49], v[50:51]
	v_add_f32_e32 v32, 1.0, v32
	v_mul_f32_e32 v40, v48, v49
	v_rcp_f32_e32 v48, v32
	v_add_f32_e32 v32, 1.0, v36
	v_rcp_f32_e32 v49, v32
	v_mul_f32_e32 v32, 0x3d372713, v41
	v_mul_f32_e32 v32, v41, v32
	v_fma_f32 v32, v41, v32, v41
	v_mul_f32_e32 v32, 0xc0135761, v32
	v_mul_f32_e32 v36, 0xbfb8aa3b, v33
	v_exp_f32_e32 v32, v32
	v_exp_f32_e32 v50, v36
	v_mov_b32_e32 v36, v45
	v_pk_mul_f32 v[36:37], v[36:37], v[48:49]
	v_add_f32_e32 v32, 1.0, v32
	v_mul_f32_e32 v48, v36, v37
	v_mul_f32_e32 v36, 0x3d372713, v46
	v_mul_f32_e32 v36, v46, v36
	v_fma_f32 v36, v46, v36, v46
	v_rcp_f32_e32 v44, v32
	v_add_f32_e32 v32, 1.0, v50
	v_mul_f32_e32 v36, 0xc0135761, v36
	v_rcp_f32_e32 v45, v32
	v_mul_f32_e32 v37, 0xbfb8aa3b, v38
	v_exp_f32_e32 v36, v36
	v_exp_f32_e32 v37, v37
	v_mov_b32_e32 v32, v41
	v_pk_mul_f32 v[32:33], v[32:33], v[44:45]
	v_mul_f32_e32 v44, 0xbfb8aa3b, v34
	v_mul_f32_e32 v41, v32, v33
	v_add_f32_e32 v32, 1.0, v36
	v_add_f32_e32 v33, 1.0, v37
	v_mov_b32_e32 v37, v38
	v_mul_f32_e32 v38, 0x3d372713, v42
	v_rcp_f32_e32 v32, v32
	v_rcp_f32_e32 v33, v33
	v_mul_f32_e32 v38, v42, v38
	v_fma_f32 v38, v42, v38, v42
	v_exp_f32_e32 v44, v44
	v_mul_f32_e32 v38, 0xc0135761, v38
	v_mov_b32_e32 v36, v46
	v_exp_f32_e32 v38, v38
	v_pk_mul_f32 v[32:33], v[36:37], v[32:33]
	v_add_f32_e32 v37, 1.0, v44
	v_mul_f32_e32 v44, v32, v33
	v_mov_b32_e32 v33, v34
	v_mul_f32_e32 v34, 0x3d372713, v47
	v_mul_f32_e32 v34, v47, v34
	v_fma_f32 v34, v47, v34, v47
	v_add_f32_e32 v36, 1.0, v38
	v_mul_f32_e32 v34, 0xc0135761, v34
	v_rcp_f32_e32 v36, v36
	v_rcp_f32_e32 v37, v37
	v_exp_f32_e32 v34, v34
	v_mov_b32_e32 v32, v42
	v_pk_mul_f32 v[32:33], v[32:33], v[36:37]
	v_mul_f32_e32 v36, 0xbfb8aa3b, v39
	v_mul_f32_e32 v42, v32, v33
	v_add_f32_e32 v32, 1.0, v34
	v_mul_f32_e32 v34, 0x3d372713, v43
	v_exp_f32_e32 v36, v36
	v_mul_f32_e32 v34, v43, v34
	v_fma_f32 v34, v43, v34, v43
	v_mul_f32_e32 v34, 0xc0135761, v34
	v_add_f32_e32 v33, 1.0, v36
	v_exp_f32_e32 v34, v34
	v_mul_f32_e32 v36, 0xbfb8aa3b, v35
	v_exp_f32_e32 v37, v36
	v_rcp_f32_e32 v32, v32
	v_add_f32_e32 v34, 1.0, v34
	v_rcp_f32_e32 v33, v33
	v_rcp_f32_e32 v36, v34
	v_add_f32_e32 v34, 1.0, v37
	v_rcp_f32_e32 v37, v34
	v_mov_b32_e32 v38, v47
	v_pk_mul_f32 v[32:33], v[38:39], v[32:33]
	v_mov_b32_e32 v34, v43
	v_mul_f32_e32 v38, v32, v33
	v_pk_mul_f32 v[32:33], v[34:35], v[36:37]
; __device__ __forceinline__ float silu_f(float v) { return v * fast_sigmoid(v); }
; __device__ __forceinline__ float gelu_f(float v) { const float u = 1.5957691216057308f * (v + 0.044715f * v * v * v); return v * fast_sigmoid(u); }
; __device__ __forceinline__ u32x4 pack8(const f32x4 a, const f32x4 b) { u32x4 w; w.x = cvt_pk_bf16(a[0], a[1]); w.y = cvt_pk_bf16(a[2], a[3]); w.z = cvt_pk_bf16(b[0], b[1]); w.w = cvt_pk_bf16(b[2], b[3]); return w; }
;     __device__ __forceinline__ void operator()(const Acc& acc, const Unit& u, int wr, int wc, int fr, int fq) const {
;         if (u.pn < 16) {
;             const int cb = u.pn * 128 + wc * 32 + 8 * fq;
; #pragma unroll
;             for (int ai = 0; ai < 2; ++ai)
; #pragma unroll
;                 for (int m = 0; m < 4; ++m) {
;                     const int row = u.pm * 256 + ai * 128 + wr * 64 + m * 16 + fr;
;                     f32x4 a0 = acc[ai][0][m][0], a1 = acc[ai][0][m][1]; const f32x4 z0 = acc[ai][1][m][0], z1 = acc[ai][1][m][1];
; #pragma unroll
;                     for (int j = 0; j < 4; ++j) { a0[j] = gelu_f(a0[j]) * silu_f(z0[j]); a1[j] = gelu_f(a1[j]) * silu_f(z1[j]); }
;                     *(u32x4*)(UZ + (size_t)row * DM + cb) = pack8(a0, a1);
;                 }
	v_add_u32_e32 v36, 0x90, v146
	v_mul_f32_e32 v35, v32, v33
	v_cvt_pk_bf16_f32 v32, v52, v48
	v_cvt_pk_bf16_f32 v33, v44, v38
	v_mul_f32_e32 v38, 0x3d372713, v28
	v_mul_f32_e32 v38, v28, v38
	v_fma_f32 v38, v28, v38, v28
	v_mul_f32_e32 v38, 0xc0135761, v38
	v_mul_f32_e32 v39, 0xbfb8aa3b, v20
	v_ashrrev_i32_e32 v37, 31, v36
	v_exp_f32_e32 v38, v38
	v_exp_f32_e32 v39, v39
	v_lshlrev_b64 v[36:37], 12, v[36:37]
	v_lshl_add_u64 v[36:37], s[8:9], 0, v[36:37]
	v_cvt_pk_bf16_f32 v34, v40, v41
	v_cvt_pk_bf16_f32 v35, v42, v35
	v_lshl_add_u64 v[36:37], v[36:37], 0, v[112:113]
	global_store_dwordx4 v[36:37], v[32:35], off
	s_nop 1
	v_add_f32_e32 v32, 1.0, v38
	v_add_f32_e32 v33, 1.0, v39
	v_mov_b32_e32 v35, v20
	v_mul_f32_e32 v20, 0x3d372713, v24
	v_rcp_f32_e32 v32, v32
	v_rcp_f32_e32 v33, v33
	v_mul_f32_e32 v20, v24, v20
	v_fma_f32 v20, v24, v20, v24
	v_mul_f32_e32 v20, 0xc0135761, v20
	v_mov_b32_e32 v34, v28
	v_exp_f32_e32 v20, v20
	v_mul_f32_e32 v28, 0xbfb8aa3b, v16
	v_pk_mul_f32 v[32:33], v[34:35], v[32:33]
	v_exp_f32_e32 v28, v28
	v_mul_f32_e32 v36, v32, v33
	v_mov_b32_e32 v33, v16
	v_mul_f32_e32 v16, 0x3d372713, v29
	v_mul_f32_e32 v16, v29, v16
	v_fma_f32 v16, v29, v16, v29
	v_add_f32_e32 v20, 1.0, v20
	v_mul_f32_e32 v16, 0xc0135761, v16
	v_rcp_f32_e32 v34, v20
	v_add_f32_e32 v20, 1.0, v28
	v_rcp_f32_e32 v35, v20
	v_exp_f32_e32 v16, v16
	v_mul_f32_e32 v20, 0xbfb8aa3b, v21
	v_exp_f32_e32 v20, v20
	v_mov_b32_e32 v32, v24
	v_pk_mul_f32 v[32:33], v[32:33], v[34:35]
	v_add_f32_e32 v16, 1.0, v16
	v_mul_f32_e32 v24, v32, v33
	v_rcp_f32_e32 v32, v16
	v_add_f32_e32 v16, 1.0, v20
	v_rcp_f32_e32 v33, v16
	v_mul_f32_e32 v16, 0x3d372713, v25
	v_mul_f32_e32 v16, v25, v16
	v_fma_f32 v16, v25, v16, v25
	v_mul_f32_e32 v16, 0xc0135761, v16
	v_mul_f32_e32 v20, 0xbfb8aa3b, v17
	v_exp_f32_e32 v16, v16
	v_exp_f32_e32 v34, v20
	v_mov_b32_e32 v20, v29
	v_pk_mul_f32 v[20:21], v[20:21], v[32:33]
	v_add_f32_e32 v16, 1.0, v16
	v_mul_f32_e32 v32, v20, v21
	v_mul_f32_e32 v20, 0x3d372713, v30
	v_mul_f32_e32 v20, v30, v20
	v_fma_f32 v20, v30, v20, v30
	v_rcp_f32_e32 v28, v16
	v_add_f32_e32 v16, 1.0, v34
	v_mul_f32_e32 v20, 0xc0135761, v20
	v_rcp_f32_e32 v29, v16
	v_mul_f32_e32 v21, 0xbfb8aa3b, v22
	v_exp_f32_e32 v20, v20
	v_exp_f32_e32 v21, v21
	v_mov_b32_e32 v16, v25
	v_pk_mul_f32 v[16:17], v[16:17], v[28:29]
	v_mul_f32_e32 v28, 0xbfb8aa3b, v18
	v_mul_f32_e32 v25, v16, v17
	v_add_f32_e32 v16, 1.0, v20
	v_add_f32_e32 v17, 1.0, v21
	v_mov_b32_e32 v21, v22
	v_mul_f32_e32 v22, 0x3d372713, v26
	v_rcp_f32_e32 v16, v16
	v_rcp_f32_e32 v17, v17
	v_mul_f32_e32 v22, v26, v22
	v_fma_f32 v22, v26, v22, v26
	v_exp_f32_e32 v28, v28
	v_mul_f32_e32 v22, 0xc0135761, v22
	v_mov_b32_e32 v20, v30
	v_exp_f32_e32 v22, v22
	v_pk_mul_f32 v[16:17], v[20:21], v[16:17]
	v_add_f32_e32 v21, 1.0, v28
	v_mul_f32_e32 v28, v16, v17
	v_mov_b32_e32 v17, v18
	v_mul_f32_e32 v18, 0x3d372713, v31
	v_mul_f32_e32 v18, v31, v18
	v_fma_f32 v18, v31, v18, v31
	v_add_f32_e32 v20, 1.0, v22
	v_mul_f32_e32 v18, 0xc0135761, v18
	v_rcp_f32_e32 v20, v20
	v_rcp_f32_e32 v21, v21
	v_exp_f32_e32 v18, v18
	v_mov_b32_e32 v16, v26
	v_pk_mul_f32 v[16:17], v[16:17], v[20:21]
	v_mul_f32_e32 v20, 0xbfb8aa3b, v23
	v_mul_f32_e32 v26, v16, v17
	v_add_f32_e32 v16, 1.0, v18
	v_mul_f32_e32 v18, 0x3d372713, v27
	v_exp_f32_e32 v20, v20
	v_mul_f32_e32 v18, v27, v18
	v_fma_f32 v18, v27, v18, v27
	v_mul_f32_e32 v18, 0xc0135761, v18
	v_add_f32_e32 v17, 1.0, v20
	v_exp_f32_e32 v18, v18
	v_mul_f32_e32 v20, 0xbfb8aa3b, v19
	v_exp_f32_e32 v21, v20
	v_rcp_f32_e32 v16, v16
	v_add_f32_e32 v18, 1.0, v18
	v_rcp_f32_e32 v17, v17
	v_rcp_f32_e32 v20, v18
	v_add_f32_e32 v18, 1.0, v21
	v_rcp_f32_e32 v21, v18
	v_mov_b32_e32 v22, v31
	v_pk_mul_f32 v[16:17], v[22:23], v[16:17]
	v_mov_b32_e32 v18, v27
	v_mul_f32_e32 v22, v16, v17
	v_pk_mul_f32 v[16:17], v[18:19], v[20:21]
	v_add_u32_e32 v20, 0xa0, v146
	v_mul_f32_e32 v19, v16, v17
	v_cvt_pk_bf16_f32 v16, v36, v32
	v_cvt_pk_bf16_f32 v17, v28, v22
; __device__ __forceinline__ float silu_f(float v) { return v * fast_sigmoid(v); }
; __device__ __forceinline__ float gelu_f(float v) { const float u = 1.5957691216057308f * (v + 0.044715f * v * v * v); return v * fast_sigmoid(u); }
; #define PG8_BAR __builtin_amdgcn_s_barrier()
; __device__ __forceinline__ u32x4 pack8(const f32x4 a, const f32x4 b) { u32x4 w; w.x = cvt_pk_bf16(a[0], a[1]); w.y = cvt_pk_bf16(a[2], a[3]); w.z = cvt_pk_bf16(b[0], b[1]); w.w = cvt_pk_bf16(b[2], b[3]); return w; }
; template <class Epi, bool ALIGN_EPI = false, bool SP2 = true>
; __device__ __forceinline__ void gemm_phase(LAS unsigned char* lds, const Gemm g, const StaticOrder& S, const Epi& E) {
;     ...
;         if constexpr (!Epi::AFTER_DRAIN) E(acc, cur, wr, wc, fr, fq);
;         if (!has_next) break;
; #pragma unroll
;         for (int a = 0; a < 2; ++a)
; #pragma unroll
;             for (int b = 0; b < 2; ++b)
; #pragma unroll
;                 for (int m = 0; m < 4; ++m)
; #pragma unroll
;                     for (int n = 0; n < 2; ++n) acc[a][b][m][n] = (f32x4){0.f, 0.f, 0.f, 0.f};
;         cur = nxt; cA = nA; cB = nB; ++ui;
;         if constexpr (ALIGN_EPI) { if (wr == 1) PG8_BAR; }
;     }
;     __device__ __forceinline__ void operator()(const Acc& acc, const Unit& u, int wr, int wc, int fr, int fq) const {
;         if (u.pn < 16) {
;             const int cb = u.pn * 128 + wc * 32 + 8 * fq;
; #pragma unroll
;             for (int ai = 0; ai < 2; ++ai)
; #pragma unroll
;                 for (int m = 0; m < 4; ++m) {
;                     const int row = u.pm * 256 + ai * 128 + wr * 64 + m * 16 + fr;
;                     f32x4 a0 = acc[ai][0][m][0], a1 = acc[ai][0][m][1]; const f32x4 z0 = acc[ai][1][m][0], z1 = acc[ai][1][m][1];
; #pragma unroll
;                     for (int j = 0; j < 4; ++j) { a0[j] = gelu_f(a0[j]) * silu_f(z0[j]); a1[j] = gelu_f(a1[j]) * silu_f(z1[j]); }
;                     *(u32x4*)(UZ + (size_t)row * DM + cb) = pack8(a0, a1);
;                 }
	v_mul_f32_e32 v22, 0x3d372713, v12
	v_mul_f32_e32 v22, v12, v22
	v_fma_f32 v22, v12, v22, v12
	v_mul_f32_e32 v22, 0xc0135761, v22
	v_mul_f32_e32 v23, 0xbfb8aa3b, v4
	v_ashrrev_i32_e32 v21, 31, v20
	v_exp_f32_e32 v22, v22
	v_exp_f32_e32 v23, v23
	v_lshlrev_b64 v[20:21], 12, v[20:21]
	v_lshl_add_u64 v[20:21], s[8:9], 0, v[20:21]
	v_cvt_pk_bf16_f32 v18, v24, v25
	v_cvt_pk_bf16_f32 v19, v26, v19
	v_lshl_add_u64 v[20:21], v[20:21], 0, v[112:113]
	global_store_dwordx4 v[20:21], v[16:19], off
	s_nop 1
	v_add_f32_e32 v16, 1.0, v22
	v_add_f32_e32 v17, 1.0, v23
	v_mov_b32_e32 v19, v4
	v_mul_f32_e32 v4, 0x3d372713, v8
	v_rcp_f32_e32 v16, v16
	v_rcp_f32_e32 v17, v17
	v_mul_f32_e32 v4, v8, v4
	v_fma_f32 v4, v8, v4, v8
	v_mul_f32_e32 v4, 0xc0135761, v4
	v_mov_b32_e32 v18, v12
	v_exp_f32_e32 v4, v4
	v_mul_f32_e32 v12, 0xbfb8aa3b, v0
	v_pk_mul_f32 v[16:17], v[18:19], v[16:17]
	v_exp_f32_e32 v12, v12
	v_mul_f32_e32 v20, v16, v17
	v_mov_b32_e32 v17, v0
	v_mul_f32_e32 v0, 0x3d372713, v13
	v_mul_f32_e32 v0, v13, v0
	v_fma_f32 v0, v13, v0, v13
	v_add_f32_e32 v4, 1.0, v4
	v_mul_f32_e32 v0, 0xc0135761, v0
	v_rcp_f32_e32 v18, v4
	v_add_f32_e32 v4, 1.0, v12
	v_rcp_f32_e32 v19, v4
	v_exp_f32_e32 v0, v0
	v_mul_f32_e32 v4, 0xbfb8aa3b, v5
	v_exp_f32_e32 v4, v4
	v_mov_b32_e32 v16, v8
	v_pk_mul_f32 v[16:17], v[16:17], v[18:19]
	v_add_f32_e32 v0, 1.0, v0
	v_mul_f32_e32 v8, v16, v17
	v_rcp_f32_e32 v16, v0
	v_add_f32_e32 v0, 1.0, v4
	v_rcp_f32_e32 v17, v0
	v_mul_f32_e32 v0, 0x3d372713, v9
	v_mul_f32_e32 v0, v9, v0
	v_fma_f32 v0, v9, v0, v9
	v_mul_f32_e32 v0, 0xc0135761, v0
	v_mul_f32_e32 v4, 0xbfb8aa3b, v1
	v_exp_f32_e32 v0, v0
	v_exp_f32_e32 v18, v4
	v_mov_b32_e32 v4, v13
	v_pk_mul_f32 v[4:5], v[4:5], v[16:17]
	v_add_f32_e32 v0, 1.0, v0
	v_mul_f32_e32 v16, v4, v5
	v_mul_f32_e32 v4, 0x3d372713, v14
	v_mul_f32_e32 v4, v14, v4
	v_fma_f32 v4, v14, v4, v14
	v_rcp_f32_e32 v12, v0
	v_add_f32_e32 v0, 1.0, v18
	v_mul_f32_e32 v4, 0xc0135761, v4
	v_rcp_f32_e32 v13, v0
	v_mul_f32_e32 v5, 0xbfb8aa3b, v6
	v_exp_f32_e32 v4, v4
	v_exp_f32_e32 v5, v5
	v_mov_b32_e32 v0, v9
	v_pk_mul_f32 v[0:1], v[0:1], v[12:13]
	v_mul_f32_e32 v12, 0xbfb8aa3b, v2
	v_mul_f32_e32 v9, v0, v1
	v_add_f32_e32 v0, 1.0, v4
	v_add_f32_e32 v1, 1.0, v5
	v_mov_b32_e32 v5, v6
	v_mul_f32_e32 v6, 0x3d372713, v10
	v_rcp_f32_e32 v0, v0
	v_rcp_f32_e32 v1, v1
	v_mul_f32_e32 v6, v10, v6
	v_fma_f32 v6, v10, v6, v10
	v_exp_f32_e32 v12, v12
	v_mul_f32_e32 v6, 0xc0135761, v6
	v_mov_b32_e32 v4, v14
	v_exp_f32_e32 v6, v6
	v_pk_mul_f32 v[0:1], v[4:5], v[0:1]
	v_add_f32_e32 v5, 1.0, v12
	v_mul_f32_e32 v12, v0, v1
	v_mov_b32_e32 v1, v2
	v_mul_f32_e32 v2, 0x3d372713, v15
	v_mul_f32_e32 v2, v15, v2
	v_fma_f32 v2, v15, v2, v15
	v_add_f32_e32 v4, 1.0, v6
	v_mul_f32_e32 v2, 0xc0135761, v2
	v_rcp_f32_e32 v4, v4
	v_rcp_f32_e32 v5, v5
	v_exp_f32_e32 v2, v2
	v_mov_b32_e32 v0, v10
	v_pk_mul_f32 v[0:1], v[0:1], v[4:5]
	v_mul_f32_e32 v4, 0xbfb8aa3b, v7
	v_mul_f32_e32 v10, v0, v1
	v_add_f32_e32 v0, 1.0, v2
	v_mul_f32_e32 v2, 0x3d372713, v11
	v_exp_f32_e32 v4, v4
	v_mul_f32_e32 v2, v11, v2
	v_fma_f32 v2, v11, v2, v11
	v_mul_f32_e32 v2, 0xc0135761, v2
	v_add_f32_e32 v1, 1.0, v4
	v_exp_f32_e32 v2, v2
	v_mul_f32_e32 v4, 0xbfb8aa3b, v3
	v_exp_f32_e32 v5, v4
	v_rcp_f32_e32 v0, v0
	v_add_f32_e32 v2, 1.0, v2
	v_rcp_f32_e32 v1, v1
	v_rcp_f32_e32 v4, v2
	v_add_f32_e32 v2, 1.0, v5
	v_rcp_f32_e32 v5, v2
	v_mov_b32_e32 v6, v15
	v_pk_mul_f32 v[0:1], v[6:7], v[0:1]
	v_mov_b32_e32 v2, v11
	v_mul_f32_e32 v6, v0, v1
	v_pk_mul_f32 v[0:1], v[2:3], v[4:5]
	v_add_u32_e32 v4, 0xb0, v146
	v_ashrrev_i32_e32 v5, 31, v4
	v_lshlrev_b64 v[4:5], 12, v[4:5]
	v_lshl_add_u64 v[4:5], s[8:9], 0, v[4:5]
	v_mul_f32_e32 v3, v0, v1
	v_lshl_add_u64 v[4:5], v[4:5], 0, v[112:113]
	v_cvt_pk_bf16_f32 v0, v20, v16
	v_cvt_pk_bf16_f32 v1, v12, v6
	v_cvt_pk_bf16_f32 v2, v8, v9
	v_cvt_pk_bf16_f32 v3, v10, v3
	global_store_dwordx4 v[4:5], v[0:3], off
	s_andn2_b64 vcc, exec, s[6:7]
	s_mov_b64 s[6:7], -1
	s_cbranch_vccnz .LBB0_151
